# v136 + VM8 (pair GEMM k-loops wait only for the previous half-step's A-tile DMA pieces)
# baseline (speedup 1.0000x reference)
.Lg1_loop:
	ds_read_b128 v[92:95], v84 offset:0
	ds_read_b128 v[96:99], v84 offset:4096
	ds_read_b128 v[188:191], v85 offset:0
	ds_read_b128 v[192:195], v85 offset:4096
	ds_read_b128 v[100:103], v86 offset:0
	ds_read_b128 v[144:147], v86 offset:4096
	ds_read_b128 v[212:215], v87 offset:0
	ds_read_b128 v[216:219], v87 offset:4096
	ds_read_b128 v[148:151], v88 offset:0
	ds_read_b128 v[152:155], v88 offset:4096
	ds_read_b128 v[220:223], v89 offset:0
	ds_read_b128 v[224:227], v89 offset:4096
	ds_read_b128 v[180:183], v90 offset:0
	ds_read_b128 v[184:187], v90 offset:4096
	ds_read_b128 v[228:231], v91 offset:0
	ds_read_b128 v[252:255], v91 offset:4096
	s_waitcnt lgkmcnt(12)
	v_mfma_f32_32x32x16_bf16 v[18:33], v[92:95], v[188:191], v[18:33]
	v_mfma_f32_32x32x16_bf16 v[50:65], v[92:95], v[192:195], v[50:65]
	v_mfma_f32_32x32x16_bf16 v[2:17], v[96:99], v[188:191], v[2:17]
	v_mfma_f32_32x32x16_bf16 v[34:49], v[96:99], v[192:195], v[34:49]
	s_waitcnt lgkmcnt(0)
	s_barrier
	s_mov_b32 m0, s1
	v_mfma_f32_32x32x16_bf16 v[18:33], v[100:103], v[212:215], v[18:33]
	global_load_lds_dwordx4 v[66:67], off
	v_mfma_f32_32x32x16_bf16 v[50:65], v[100:103], v[216:219], v[50:65]
	s_add_i32 m0, s1, 0x400
	v_mfma_f32_32x32x16_bf16 v[2:17], v[144:147], v[212:215], v[2:17]
	global_load_lds_dwordx4 v[70:71], off
	s_add_i32 m0, s1, 0x800
	v_mfma_f32_32x32x16_bf16 v[34:49], v[144:147], v[216:219], v[34:49]
	global_load_lds_dwordx4 v[74:75], off
	v_mfma_f32_32x32x16_bf16 v[18:33], v[148:151], v[220:223], v[18:33]
	s_add_i32 m0, s1, 0xc00
	v_mfma_f32_32x32x16_bf16 v[50:65], v[148:151], v[224:227], v[50:65]
	global_load_lds_dwordx4 v[78:79], off
	v_mfma_f32_32x32x16_bf16 v[2:17], v[152:155], v[220:223], v[2:17]
	v_mfma_f32_32x32x16_bf16 v[34:49], v[152:155], v[224:227], v[34:49]
	s_mov_b32 m0, s8
	v_mfma_f32_32x32x16_bf16 v[18:33], v[180:183], v[228:231], v[18:33]
	global_load_lds_dwordx4 v[68:69], off
	v_lshl_add_u64 v[68:69], v[68:69], 0, s[34:35]
	s_mov_b32 m0, s9
	v_mfma_f32_32x32x16_bf16 v[50:65], v[180:183], v[252:255], v[50:65]
	global_load_lds_dwordx4 v[72:73], off
	v_lshl_add_u64 v[72:73], v[72:73], 0, s[34:35]
	v_mfma_f32_32x32x16_bf16 v[2:17], v[184:187], v[228:231], v[2:17]
	v_mfma_f32_32x32x16_bf16 v[34:49], v[184:187], v[252:255], v[34:49]
	s_waitcnt vmcnt(8)
	s_barrier
	ds_read_b128 v[92:95], v84 offset:32768
	ds_read_b128 v[96:99], v84 offset:36864
	ds_read_b128 v[100:103], v86 offset:32768
	ds_read_b128 v[144:147], v86 offset:36864
	ds_read_b128 v[148:151], v88 offset:32768
	ds_read_b128 v[152:155], v88 offset:36864
	ds_read_b128 v[180:183], v90 offset:32768
	ds_read_b128 v[184:187], v90 offset:36864
	s_waitcnt lgkmcnt(6)
	v_mfma_f32_32x32x16_bf16 v[104:119], v[92:95], v[188:191], v[104:119]
	v_mfma_f32_32x32x16_bf16 v[128:143], v[92:95], v[192:195], v[128:143]
	v_mfma_f32_32x32x16_bf16 v[196:211], v[96:99], v[188:191], v[196:211]
	v_mfma_f32_32x32x16_bf16 v[236:251], v[96:99], v[192:195], v[236:251]
	s_waitcnt lgkmcnt(0)
	s_barrier
	s_mov_b32 m0, s6
	v_lshl_add_u64 v[82:83], v[66:67], 0, s[26:27]
	v_mfma_f32_32x32x16_bf16 v[104:119], v[100:103], v[212:215], v[104:119]
	global_load_lds_dwordx4 v[82:83], off
	v_lshl_add_u64 v[66:67], v[66:67], 0, s[34:35]
	v_mfma_f32_32x32x16_bf16 v[128:143], v[100:103], v[216:219], v[128:143]
	s_mov_b32 m0, s13
	v_lshl_add_u64 v[82:83], v[70:71], 0, s[26:27]
	v_mfma_f32_32x32x16_bf16 v[196:211], v[144:147], v[212:215], v[196:211]
	global_load_lds_dwordx4 v[82:83], off
	v_lshl_add_u64 v[70:71], v[70:71], 0, s[34:35]
	s_mov_b32 m0, s15
	v_lshl_add_u64 v[82:83], v[74:75], 0, s[26:27]
	v_mfma_f32_32x32x16_bf16 v[236:251], v[144:147], v[216:219], v[236:251]
	global_load_lds_dwordx4 v[82:83], off
	v_lshl_add_u64 v[74:75], v[74:75], 0, s[34:35]
	v_mfma_f32_32x32x16_bf16 v[104:119], v[148:151], v[220:223], v[104:119]
	s_mov_b32 m0, s17
	v_lshl_add_u64 v[82:83], v[78:79], 0, s[26:27]
	v_mfma_f32_32x32x16_bf16 v[128:143], v[148:151], v[224:227], v[128:143]
	global_load_lds_dwordx4 v[82:83], off
	v_lshl_add_u64 v[78:79], v[78:79], 0, s[34:35]
	v_mfma_f32_32x32x16_bf16 v[196:211], v[152:155], v[220:223], v[196:211]
	v_mfma_f32_32x32x16_bf16 v[236:251], v[152:155], v[224:227], v[236:251]
	s_mov_b32 m0, s10
	v_mfma_f32_32x32x16_bf16 v[104:119], v[180:183], v[228:231], v[104:119]
	global_load_lds_dwordx4 v[76:77], off
	v_lshl_add_u64 v[76:77], v[76:77], 0, s[34:35]
	s_mov_b32 m0, s11
	v_mfma_f32_32x32x16_bf16 v[128:143], v[180:183], v[252:255], v[128:143]
	global_load_lds_dwordx4 v[80:81], off
	v_lshl_add_u64 v[80:81], v[80:81], 0, s[34:35]
	v_mfma_f32_32x32x16_bf16 v[196:211], v[184:187], v[228:231], v[196:211]
	v_mfma_f32_32x32x16_bf16 v[236:251], v[184:187], v[252:255], v[236:251]
	s_waitcnt vmcnt(8)
	s_barrier
	ds_read_b128 v[92:95], v84 offset:0
	ds_read_b128 v[96:99], v84 offset:4096
	ds_read_b128 v[188:191], v85 offset:32768
	ds_read_b128 v[192:195], v85 offset:36864
	ds_read_b128 v[100:103], v86 offset:0
	ds_read_b128 v[144:147], v86 offset:4096
	ds_read_b128 v[212:215], v87 offset:32768
	ds_read_b128 v[216:219], v87 offset:36864
	ds_read_b128 v[148:151], v88 offset:0
	ds_read_b128 v[152:155], v88 offset:4096
	ds_read_b128 v[220:223], v89 offset:32768
	ds_read_b128 v[224:227], v89 offset:36864
	ds_read_b128 v[180:183], v90 offset:0
	ds_read_b128 v[184:187], v90 offset:4096
	ds_read_b128 v[228:231], v91 offset:32768
	ds_read_b128 v[252:255], v91 offset:36864
	s_waitcnt lgkmcnt(12)
	v_mfma_f32_32x32x16_bf16 v[18:33], v[92:95], v[188:191], v[18:33]
	v_mfma_f32_32x32x16_bf16 v[50:65], v[92:95], v[192:195], v[50:65]
	v_mfma_f32_32x32x16_bf16 v[2:17], v[96:99], v[188:191], v[2:17]
	v_mfma_f32_32x32x16_bf16 v[34:49], v[96:99], v[192:195], v[34:49]
	s_waitcnt lgkmcnt(0)
	s_barrier
	s_mov_b32 m0, s1
	v_mfma_f32_32x32x16_bf16 v[18:33], v[100:103], v[212:215], v[18:33]
	global_load_lds_dwordx4 v[66:67], off
	v_mfma_f32_32x32x16_bf16 v[50:65], v[100:103], v[216:219], v[50:65]
	s_add_i32 m0, s1, 0x400
	v_mfma_f32_32x32x16_bf16 v[2:17], v[144:147], v[212:215], v[2:17]
	global_load_lds_dwordx4 v[70:71], off
	s_add_i32 m0, s1, 0x800
	v_mfma_f32_32x32x16_bf16 v[34:49], v[144:147], v[216:219], v[34:49]
	global_load_lds_dwordx4 v[74:75], off
	v_mfma_f32_32x32x16_bf16 v[18:33], v[148:151], v[220:223], v[18:33]
	s_add_i32 m0, s1, 0xc00
	v_mfma_f32_32x32x16_bf16 v[50:65], v[148:151], v[224:227], v[50:65]
	global_load_lds_dwordx4 v[78:79], off
	v_mfma_f32_32x32x16_bf16 v[2:17], v[152:155], v[220:223], v[2:17]
	v_mfma_f32_32x32x16_bf16 v[34:49], v[152:155], v[224:227], v[34:49]
	s_mov_b32 m0, s7
	v_mfma_f32_32x32x16_bf16 v[18:33], v[180:183], v[228:231], v[18:33]
	global_load_lds_dwordx4 v[68:69], off
	v_lshl_add_u64 v[68:69], v[68:69], 0, s[34:35]
	s_mov_b32 m0, s14
	v_mfma_f32_32x32x16_bf16 v[50:65], v[180:183], v[252:255], v[50:65]
	global_load_lds_dwordx4 v[72:73], off
	v_lshl_add_u64 v[72:73], v[72:73], 0, s[34:35]
	v_mfma_f32_32x32x16_bf16 v[2:17], v[184:187], v[228:231], v[2:17]
	v_mfma_f32_32x32x16_bf16 v[34:49], v[184:187], v[252:255], v[34:49]
	s_waitcnt vmcnt(8)
	s_barrier
	ds_read_b128 v[92:95], v84 offset:32768
	ds_read_b128 v[96:99], v84 offset:36864
	ds_read_b128 v[100:103], v86 offset:32768
	ds_read_b128 v[144:147], v86 offset:36864
	ds_read_b128 v[148:151], v88 offset:32768
	ds_read_b128 v[152:155], v88 offset:36864
	ds_read_b128 v[180:183], v90 offset:32768
	ds_read_b128 v[184:187], v90 offset:36864
	s_waitcnt lgkmcnt(6)
	v_mfma_f32_32x32x16_bf16 v[104:119], v[92:95], v[188:191], v[104:119]
	v_mfma_f32_32x32x16_bf16 v[128:143], v[92:95], v[192:195], v[128:143]
	v_mfma_f32_32x32x16_bf16 v[196:211], v[96:99], v[188:191], v[196:211]
	v_mfma_f32_32x32x16_bf16 v[236:251], v[96:99], v[192:195], v[236:251]
	s_waitcnt lgkmcnt(0)
	s_barrier
	s_mov_b32 m0, s6
	v_lshl_add_u64 v[82:83], v[66:67], 0, s[26:27]
	v_mfma_f32_32x32x16_bf16 v[104:119], v[100:103], v[212:215], v[104:119]
	global_load_lds_dwordx4 v[82:83], off
	v_lshl_add_u64 v[66:67], v[66:67], 0, s[34:35]
	v_mfma_f32_32x32x16_bf16 v[128:143], v[100:103], v[216:219], v[128:143]
	s_mov_b32 m0, s13
	v_lshl_add_u64 v[82:83], v[70:71], 0, s[26:27]
	v_mfma_f32_32x32x16_bf16 v[196:211], v[144:147], v[212:215], v[196:211]
	global_load_lds_dwordx4 v[82:83], off
	v_lshl_add_u64 v[70:71], v[70:71], 0, s[34:35]
	s_mov_b32 m0, s15
	v_lshl_add_u64 v[82:83], v[74:75], 0, s[26:27]
	v_mfma_f32_32x32x16_bf16 v[236:251], v[144:147], v[216:219], v[236:251]
	global_load_lds_dwordx4 v[82:83], off
	v_lshl_add_u64 v[74:75], v[74:75], 0, s[34:35]
	v_mfma_f32_32x32x16_bf16 v[104:119], v[148:151], v[220:223], v[104:119]
	s_mov_b32 m0, s17
	v_lshl_add_u64 v[82:83], v[78:79], 0, s[26:27]
	v_mfma_f32_32x32x16_bf16 v[128:143], v[148:151], v[224:227], v[128:143]
	global_load_lds_dwordx4 v[82:83], off
	v_lshl_add_u64 v[78:79], v[78:79], 0, s[34:35]
	v_mfma_f32_32x32x16_bf16 v[196:211], v[152:155], v[220:223], v[196:211]
	v_mfma_f32_32x32x16_bf16 v[236:251], v[152:155], v[224:227], v[236:251]
	s_mov_b32 m0, s16
	v_mfma_f32_32x32x16_bf16 v[104:119], v[180:183], v[228:231], v[104:119]
	global_load_lds_dwordx4 v[76:77], off
	v_lshl_add_u64 v[76:77], v[76:77], 0, s[34:35]
	s_mov_b32 m0, s25
	v_mfma_f32_32x32x16_bf16 v[128:143], v[180:183], v[252:255], v[128:143]
	global_load_lds_dwordx4 v[80:81], off
	v_lshl_add_u64 v[80:81], v[80:81], 0, s[34:35]
	v_mfma_f32_32x32x16_bf16 v[196:211], v[184:187], v[228:231], v[196:211]
	v_mfma_f32_32x32x16_bf16 v[236:251], v[184:187], v[252:255], v[236:251]
	s_waitcnt vmcnt(8)
	s_barrier
	s_add_i32 s12, s12, 2
	s_cmp_lt_u32 s12, 14
	s_cbranch_scc1 .Lg1_loop
	ds_read_b128 v[92:95], v84 offset:0
	ds_read_b128 v[96:99], v84 offset:4096
	ds_read_b128 v[188:191], v85 offset:0
	ds_read_b128 v[192:195], v85 offset:4096
	ds_read_b128 v[100:103], v86 offset:0
	ds_read_b128 v[144:147], v86 offset:4096
	ds_read_b128 v[212:215], v87 offset:0
	ds_read_b128 v[216:219], v87 offset:4096
	ds_read_b128 v[148:151], v88 offset:0
	ds_read_b128 v[152:155], v88 offset:4096
	ds_read_b128 v[220:223], v89 offset:0
	ds_read_b128 v[224:227], v89 offset:4096
	ds_read_b128 v[180:183], v90 offset:0
	ds_read_b128 v[184:187], v90 offset:4096
	ds_read_b128 v[228:231], v91 offset:0
	ds_read_b128 v[252:255], v91 offset:4096
	s_waitcnt lgkmcnt(12)
	v_mfma_f32_32x32x16_bf16 v[18:33], v[92:95], v[188:191], v[18:33]
	v_mfma_f32_32x32x16_bf16 v[50:65], v[92:95], v[192:195], v[50:65]
	v_mfma_f32_32x32x16_bf16 v[2:17], v[96:99], v[188:191], v[2:17]
	v_mfma_f32_32x32x16_bf16 v[34:49], v[96:99], v[192:195], v[34:49]
	s_waitcnt lgkmcnt(0)
	s_barrier
	s_mov_b32 m0, s1
	v_mfma_f32_32x32x16_bf16 v[18:33], v[100:103], v[212:215], v[18:33]
	global_load_lds_dwordx4 v[66:67], off
	v_mfma_f32_32x32x16_bf16 v[50:65], v[100:103], v[216:219], v[50:65]
	s_add_i32 m0, s1, 0x400
	v_mfma_f32_32x32x16_bf16 v[2:17], v[144:147], v[212:215], v[2:17]
	global_load_lds_dwordx4 v[70:71], off
	v_mfma_f32_32x32x16_bf16 v[34:49], v[144:147], v[216:219], v[34:49]
	v_mfma_f32_32x32x16_bf16 v[18:33], v[148:151], v[220:223], v[18:33]
	s_add_i32 m0, s1, 0x800
	v_mfma_f32_32x32x16_bf16 v[50:65], v[148:151], v[224:227], v[50:65]
	global_load_lds_dwordx4 v[74:75], off
	v_mfma_f32_32x32x16_bf16 v[2:17], v[152:155], v[220:223], v[2:17]
	v_mfma_f32_32x32x16_bf16 v[34:49], v[152:155], v[224:227], v[34:49]
	s_add_i32 m0, s1, 0xc00
	v_mfma_f32_32x32x16_bf16 v[18:33], v[180:183], v[228:231], v[18:33]
	global_load_lds_dwordx4 v[78:79], off
	v_mfma_f32_32x32x16_bf16 v[50:65], v[180:183], v[252:255], v[50:65]
	v_mfma_f32_32x32x16_bf16 v[2:17], v[184:187], v[228:231], v[2:17]
	v_mfma_f32_32x32x16_bf16 v[34:49], v[184:187], v[252:255], v[34:49]
	s_waitcnt vmcnt(4)
	s_barrier
	ds_read_b128 v[92:95], v84 offset:32768
	ds_read_b128 v[96:99], v84 offset:36864
	ds_read_b128 v[100:103], v86 offset:32768
	ds_read_b128 v[144:147], v86 offset:36864
	ds_read_b128 v[148:151], v88 offset:32768
	ds_read_b128 v[152:155], v88 offset:36864
	ds_read_b128 v[180:183], v90 offset:32768
	ds_read_b128 v[184:187], v90 offset:36864
	s_waitcnt lgkmcnt(6)
	v_mfma_f32_32x32x16_bf16 v[104:119], v[92:95], v[188:191], v[104:119]
	v_mfma_f32_32x32x16_bf16 v[128:143], v[92:95], v[192:195], v[128:143]
	v_mfma_f32_32x32x16_bf16 v[196:211], v[96:99], v[188:191], v[196:211]
	v_mfma_f32_32x32x16_bf16 v[236:251], v[96:99], v[192:195], v[236:251]
	s_waitcnt lgkmcnt(0)
	s_barrier
	s_mov_b32 m0, s6
	v_lshl_add_u64 v[82:83], v[66:67], 0, s[26:27]
	v_mfma_f32_32x32x16_bf16 v[104:119], v[100:103], v[212:215], v[104:119]
	global_load_lds_dwordx4 v[82:83], off
	v_lshl_add_u64 v[66:67], v[66:67], 0, s[34:35]
	v_mfma_f32_32x32x16_bf16 v[128:143], v[100:103], v[216:219], v[128:143]
	s_mov_b32 m0, s13
	v_lshl_add_u64 v[82:83], v[70:71], 0, s[26:27]
	v_mfma_f32_32x32x16_bf16 v[196:211], v[144:147], v[212:215], v[196:211]
	global_load_lds_dwordx4 v[82:83], off
	v_lshl_add_u64 v[70:71], v[70:71], 0, s[34:35]
	v_mfma_f32_32x32x16_bf16 v[236:251], v[144:147], v[216:219], v[236:251]
	v_mfma_f32_32x32x16_bf16 v[104:119], v[148:151], v[220:223], v[104:119]
	s_mov_b32 m0, s15
	v_lshl_add_u64 v[82:83], v[74:75], 0, s[26:27]
	v_mfma_f32_32x32x16_bf16 v[128:143], v[148:151], v[224:227], v[128:143]
	global_load_lds_dwordx4 v[82:83], off
	v_lshl_add_u64 v[74:75], v[74:75], 0, s[34:35]
	v_mfma_f32_32x32x16_bf16 v[196:211], v[152:155], v[220:223], v[196:211]
	v_mfma_f32_32x32x16_bf16 v[236:251], v[152:155], v[224:227], v[236:251]
	s_mov_b32 m0, s17
	v_lshl_add_u64 v[82:83], v[78:79], 0, s[26:27]
	v_mfma_f32_32x32x16_bf16 v[104:119], v[180:183], v[228:231], v[104:119]
	global_load_lds_dwordx4 v[82:83], off
	v_lshl_add_u64 v[78:79], v[78:79], 0, s[34:35]
	v_mfma_f32_32x32x16_bf16 v[128:143], v[180:183], v[252:255], v[128:143]
	v_mfma_f32_32x32x16_bf16 v[196:211], v[184:187], v[228:231], v[196:211]
	v_mfma_f32_32x32x16_bf16 v[236:251], v[184:187], v[252:255], v[236:251]
	s_waitcnt vmcnt(4)
	s_barrier
	ds_read_b128 v[92:95], v84 offset:0
	ds_read_b128 v[96:99], v84 offset:4096
	ds_read_b128 v[188:191], v85 offset:32768
	ds_read_b128 v[192:195], v85 offset:36864
	ds_read_b128 v[100:103], v86 offset:0
	ds_read_b128 v[144:147], v86 offset:4096
	ds_read_b128 v[212:215], v87 offset:32768
	ds_read_b128 v[216:219], v87 offset:36864
	ds_read_b128 v[148:151], v88 offset:0
	ds_read_b128 v[152:155], v88 offset:4096
	ds_read_b128 v[220:223], v89 offset:32768
	ds_read_b128 v[224:227], v89 offset:36864
	ds_read_b128 v[180:183], v90 offset:0
	ds_read_b128 v[184:187], v90 offset:4096
	ds_read_b128 v[228:231], v91 offset:32768
	ds_read_b128 v[252:255], v91 offset:36864
	s_waitcnt lgkmcnt(12)
	v_mfma_f32_32x32x16_bf16 v[18:33], v[92:95], v[188:191], v[18:33]
	v_mfma_f32_32x32x16_bf16 v[50:65], v[92:95], v[192:195], v[50:65]
	v_mfma_f32_32x32x16_bf16 v[2:17], v[96:99], v[188:191], v[2:17]
	v_mfma_f32_32x32x16_bf16 v[34:49], v[96:99], v[192:195], v[34:49]
	s_waitcnt lgkmcnt(0)
	s_barrier
	v_mfma_f32_32x32x16_bf16 v[18:33], v[100:103], v[212:215], v[18:33]
	v_mfma_f32_32x32x16_bf16 v[50:65], v[100:103], v[216:219], v[50:65]
	v_mfma_f32_32x32x16_bf16 v[2:17], v[144:147], v[212:215], v[2:17]
	v_mfma_f32_32x32x16_bf16 v[34:49], v[144:147], v[216:219], v[34:49]
	v_mfma_f32_32x32x16_bf16 v[18:33], v[148:151], v[220:223], v[18:33]
	v_mfma_f32_32x32x16_bf16 v[50:65], v[148:151], v[224:227], v[50:65]
	v_mfma_f32_32x32x16_bf16 v[2:17], v[152:155], v[220:223], v[2:17]
	v_mfma_f32_32x32x16_bf16 v[34:49], v[152:155], v[224:227], v[34:49]
	v_mfma_f32_32x32x16_bf16 v[18:33], v[180:183], v[228:231], v[18:33]
	v_mfma_f32_32x32x16_bf16 v[50:65], v[180:183], v[252:255], v[50:65]
	v_mfma_f32_32x32x16_bf16 v[2:17], v[184:187], v[228:231], v[2:17]
	v_mfma_f32_32x32x16_bf16 v[34:49], v[184:187], v[252:255], v[34:49]
	s_waitcnt vmcnt(0)
	s_barrier
	ds_read_b128 v[92:95], v84 offset:32768
	ds_read_b128 v[96:99], v84 offset:36864
	ds_read_b128 v[100:103], v86 offset:32768
	ds_read_b128 v[144:147], v86 offset:36864
	ds_read_b128 v[148:151], v88 offset:32768
	ds_read_b128 v[152:155], v88 offset:36864
	ds_read_b128 v[180:183], v90 offset:32768
	ds_read_b128 v[184:187], v90 offset:36864
	s_waitcnt lgkmcnt(6)
	v_mfma_f32_32x32x16_bf16 v[104:119], v[92:95], v[188:191], v[104:119]
	v_mfma_f32_32x32x16_bf16 v[128:143], v[92:95], v[192:195], v[128:143]
	v_mfma_f32_32x32x16_bf16 v[196:211], v[96:99], v[188:191], v[196:211]
	v_mfma_f32_32x32x16_bf16 v[236:251], v[96:99], v[192:195], v[236:251]
	s_waitcnt lgkmcnt(0)
	s_barrier
	v_mfma_f32_32x32x16_bf16 v[104:119], v[100:103], v[212:215], v[104:119]
	v_mfma_f32_32x32x16_bf16 v[128:143], v[100:103], v[216:219], v[128:143]
	v_mfma_f32_32x32x16_bf16 v[196:211], v[144:147], v[212:215], v[196:211]
	v_mfma_f32_32x32x16_bf16 v[236:251], v[144:147], v[216:219], v[236:251]
	v_mfma_f32_32x32x16_bf16 v[104:119], v[148:151], v[220:223], v[104:119]
	v_mfma_f32_32x32x16_bf16 v[128:143], v[148:151], v[224:227], v[128:143]
	v_mfma_f32_32x32x16_bf16 v[196:211], v[152:155], v[220:223], v[196:211]
	v_mfma_f32_32x32x16_bf16 v[236:251], v[152:155], v[224:227], v[236:251]
	v_mfma_f32_32x32x16_bf16 v[104:119], v[180:183], v[228:231], v[104:119]
	v_mfma_f32_32x32x16_bf16 v[128:143], v[180:183], v[252:255], v[128:143]
	v_mfma_f32_32x32x16_bf16 v[196:211], v[184:187], v[228:231], v[196:211]
	v_mfma_f32_32x32x16_bf16 v[236:251], v[184:187], v[252:255], v[236:251]
	s_waitcnt vmcnt(0) lgkmcnt(0)
	s_barrier
	s_branch .LBB0_187
.Lg1_loop_w1:
	ds_read_b128 v[92:95], v84 offset:0
	ds_read_b128 v[96:99], v84 offset:4096
	ds_read_b128 v[188:191], v85 offset:0
	ds_read_b128 v[192:195], v85 offset:4096
	ds_read_b128 v[100:103], v86 offset:0
	ds_read_b128 v[144:147], v86 offset:4096
	ds_read_b128 v[212:215], v87 offset:0
	ds_read_b128 v[216:219], v87 offset:4096
	ds_read_b128 v[148:151], v88 offset:0
	ds_read_b128 v[152:155], v88 offset:4096
	ds_read_b128 v[220:223], v89 offset:0
	ds_read_b128 v[224:227], v89 offset:4096
	ds_read_b128 v[180:183], v90 offset:0
	ds_read_b128 v[184:187], v90 offset:4096
	ds_read_b128 v[228:231], v91 offset:0
	ds_read_b128 v[252:255], v91 offset:4096
	s_waitcnt lgkmcnt(12)
	v_mfma_f32_32x32x16_bf16 v[18:33], v[92:95], v[188:191], v[18:33]
	v_mfma_f32_32x32x16_bf16 v[50:65], v[92:95], v[192:195], v[50:65]
	v_mfma_f32_32x32x16_bf16 v[2:17], v[96:99], v[188:191], v[2:17]
	v_mfma_f32_32x32x16_bf16 v[34:49], v[96:99], v[192:195], v[34:49]
	s_waitcnt lgkmcnt(0)
	s_barrier
	s_mov_b32 m0, s1
	v_mfma_f32_32x32x16_bf16 v[18:33], v[100:103], v[212:215], v[18:33]
	global_load_lds_dwordx4 v[66:67], off
	v_mfma_f32_32x32x16_bf16 v[50:65], v[100:103], v[216:219], v[50:65]
	s_add_i32 m0, s1, 0x400
	v_mfma_f32_32x32x16_bf16 v[2:17], v[144:147], v[212:215], v[2:17]
	global_load_lds_dwordx4 v[70:71], off
	v_mfma_f32_32x32x16_bf16 v[34:49], v[144:147], v[216:219], v[34:49]
	s_add_i32 m0, s1, 0x800
	v_mfma_f32_32x32x16_bf16 v[18:33], v[148:151], v[220:223], v[18:33]
	global_load_lds_dwordx4 v[74:75], off
	v_mfma_f32_32x32x16_bf16 v[50:65], v[148:151], v[224:227], v[50:65]
	s_add_i32 m0, s1, 0xc00
	v_mfma_f32_32x32x16_bf16 v[2:17], v[152:155], v[220:223], v[2:17]
	global_load_lds_dwordx4 v[78:79], off
	v_mfma_f32_32x32x16_bf16 v[34:49], v[152:155], v[224:227], v[34:49]
	s_mov_b32 m0, s8
	v_mfma_f32_32x32x16_bf16 v[18:33], v[180:183], v[228:231], v[18:33]
	global_load_lds_dwordx4 v[68:69], off
	v_lshl_add_u64 v[68:69], v[68:69], 0, s[34:35]
	v_mfma_f32_32x32x16_bf16 v[50:65], v[180:183], v[252:255], v[50:65]
	s_mov_b32 m0, s9
	v_mfma_f32_32x32x16_bf16 v[2:17], v[184:187], v[228:231], v[2:17]
	global_load_lds_dwordx4 v[72:73], off
	v_lshl_add_u64 v[72:73], v[72:73], 0, s[34:35]
	v_mfma_f32_32x32x16_bf16 v[34:49], v[184:187], v[252:255], v[34:49]
	s_waitcnt vmcnt(8)
	s_barrier
	ds_read_b128 v[92:95], v84 offset:32768
	ds_read_b128 v[96:99], v84 offset:36864
	ds_read_b128 v[100:103], v86 offset:32768
	ds_read_b128 v[144:147], v86 offset:36864
	ds_read_b128 v[148:151], v88 offset:32768
	ds_read_b128 v[152:155], v88 offset:36864
	ds_read_b128 v[180:183], v90 offset:32768
	ds_read_b128 v[184:187], v90 offset:36864
	s_waitcnt lgkmcnt(6)
	v_mfma_f32_32x32x16_bf16 v[104:119], v[92:95], v[188:191], v[104:119]
	v_mfma_f32_32x32x16_bf16 v[128:143], v[92:95], v[192:195], v[128:143]
	v_mfma_f32_32x32x16_bf16 v[196:211], v[96:99], v[188:191], v[196:211]
	v_mfma_f32_32x32x16_bf16 v[236:251], v[96:99], v[192:195], v[236:251]
	s_waitcnt lgkmcnt(0)
	s_barrier
	s_mov_b32 m0, s6
	v_lshl_add_u64 v[82:83], v[66:67], 0, s[26:27]
	v_mfma_f32_32x32x16_bf16 v[104:119], v[100:103], v[212:215], v[104:119]
	global_load_lds_dwordx4 v[82:83], off
	v_lshl_add_u64 v[66:67], v[66:67], 0, s[34:35]
	v_mfma_f32_32x32x16_bf16 v[128:143], v[100:103], v[216:219], v[128:143]
	s_mov_b32 m0, s13
	v_lshl_add_u64 v[82:83], v[70:71], 0, s[26:27]
	v_mfma_f32_32x32x16_bf16 v[196:211], v[144:147], v[212:215], v[196:211]
	global_load_lds_dwordx4 v[82:83], off
	v_lshl_add_u64 v[70:71], v[70:71], 0, s[34:35]
	v_mfma_f32_32x32x16_bf16 v[236:251], v[144:147], v[216:219], v[236:251]
	s_mov_b32 m0, s15
	v_lshl_add_u64 v[82:83], v[74:75], 0, s[26:27]
	v_mfma_f32_32x32x16_bf16 v[104:119], v[148:151], v[220:223], v[104:119]
	global_load_lds_dwordx4 v[82:83], off
	v_lshl_add_u64 v[74:75], v[74:75], 0, s[34:35]
	v_mfma_f32_32x32x16_bf16 v[128:143], v[148:151], v[224:227], v[128:143]
	s_mov_b32 m0, s17
	v_lshl_add_u64 v[82:83], v[78:79], 0, s[26:27]
	v_mfma_f32_32x32x16_bf16 v[196:211], v[152:155], v[220:223], v[196:211]
	global_load_lds_dwordx4 v[82:83], off
	v_lshl_add_u64 v[78:79], v[78:79], 0, s[34:35]
	v_mfma_f32_32x32x16_bf16 v[236:251], v[152:155], v[224:227], v[236:251]
	s_mov_b32 m0, s10
	v_mfma_f32_32x32x16_bf16 v[104:119], v[180:183], v[228:231], v[104:119]
	global_load_lds_dwordx4 v[76:77], off
	v_lshl_add_u64 v[76:77], v[76:77], 0, s[34:35]
	v_mfma_f32_32x32x16_bf16 v[128:143], v[180:183], v[252:255], v[128:143]
	s_mov_b32 m0, s11
	v_mfma_f32_32x32x16_bf16 v[196:211], v[184:187], v[228:231], v[196:211]
	global_load_lds_dwordx4 v[80:81], off
	v_lshl_add_u64 v[80:81], v[80:81], 0, s[34:35]
	v_mfma_f32_32x32x16_bf16 v[236:251], v[184:187], v[252:255], v[236:251]
	s_waitcnt vmcnt(8)
	s_barrier
	ds_read_b128 v[92:95], v84 offset:0
	ds_read_b128 v[96:99], v84 offset:4096
	ds_read_b128 v[188:191], v85 offset:32768
	ds_read_b128 v[192:195], v85 offset:36864
	ds_read_b128 v[100:103], v86 offset:0
	ds_read_b128 v[144:147], v86 offset:4096
	ds_read_b128 v[212:215], v87 offset:32768
	ds_read_b128 v[216:219], v87 offset:36864
	ds_read_b128 v[148:151], v88 offset:0
	ds_read_b128 v[152:155], v88 offset:4096
	ds_read_b128 v[220:223], v89 offset:32768
	ds_read_b128 v[224:227], v89 offset:36864
	ds_read_b128 v[180:183], v90 offset:0
	ds_read_b128 v[184:187], v90 offset:4096
	ds_read_b128 v[228:231], v91 offset:32768
	ds_read_b128 v[252:255], v91 offset:36864
	s_waitcnt lgkmcnt(12)
	v_mfma_f32_32x32x16_bf16 v[18:33], v[92:95], v[188:191], v[18:33]
	v_mfma_f32_32x32x16_bf16 v[50:65], v[92:95], v[192:195], v[50:65]
	v_mfma_f32_32x32x16_bf16 v[2:17], v[96:99], v[188:191], v[2:17]
	v_mfma_f32_32x32x16_bf16 v[34:49], v[96:99], v[192:195], v[34:49]
	s_waitcnt lgkmcnt(0)
	s_barrier
	s_mov_b32 m0, s1
	v_mfma_f32_32x32x16_bf16 v[18:33], v[100:103], v[212:215], v[18:33]
	global_load_lds_dwordx4 v[66:67], off
	v_mfma_f32_32x32x16_bf16 v[50:65], v[100:103], v[216:219], v[50:65]
	s_add_i32 m0, s1, 0x400
	v_mfma_f32_32x32x16_bf16 v[2:17], v[144:147], v[212:215], v[2:17]
	global_load_lds_dwordx4 v[70:71], off
	v_mfma_f32_32x32x16_bf16 v[34:49], v[144:147], v[216:219], v[34:49]
	s_add_i32 m0, s1, 0x800
	v_mfma_f32_32x32x16_bf16 v[18:33], v[148:151], v[220:223], v[18:33]
	global_load_lds_dwordx4 v[74:75], off
	v_mfma_f32_32x32x16_bf16 v[50:65], v[148:151], v[224:227], v[50:65]
	s_add_i32 m0, s1, 0xc00
	v_mfma_f32_32x32x16_bf16 v[2:17], v[152:155], v[220:223], v[2:17]
	global_load_lds_dwordx4 v[78:79], off
	v_mfma_f32_32x32x16_bf16 v[34:49], v[152:155], v[224:227], v[34:49]
	s_mov_b32 m0, s7
	v_mfma_f32_32x32x16_bf16 v[18:33], v[180:183], v[228:231], v[18:33]
	global_load_lds_dwordx4 v[68:69], off
	v_lshl_add_u64 v[68:69], v[68:69], 0, s[34:35]
	v_mfma_f32_32x32x16_bf16 v[50:65], v[180:183], v[252:255], v[50:65]
	s_mov_b32 m0, s14
	v_mfma_f32_32x32x16_bf16 v[2:17], v[184:187], v[228:231], v[2:17]
	global_load_lds_dwordx4 v[72:73], off
	v_lshl_add_u64 v[72:73], v[72:73], 0, s[34:35]
	v_mfma_f32_32x32x16_bf16 v[34:49], v[184:187], v[252:255], v[34:49]
	s_waitcnt vmcnt(8)
	s_barrier
	ds_read_b128 v[92:95], v84 offset:32768
	ds_read_b128 v[96:99], v84 offset:36864
	ds_read_b128 v[100:103], v86 offset:32768
	ds_read_b128 v[144:147], v86 offset:36864
	ds_read_b128 v[148:151], v88 offset:32768
	ds_read_b128 v[152:155], v88 offset:36864
	ds_read_b128 v[180:183], v90 offset:32768
	ds_read_b128 v[184:187], v90 offset:36864
	s_waitcnt lgkmcnt(6)
	v_mfma_f32_32x32x16_bf16 v[104:119], v[92:95], v[188:191], v[104:119]
	v_mfma_f32_32x32x16_bf16 v[128:143], v[92:95], v[192:195], v[128:143]
	v_mfma_f32_32x32x16_bf16 v[196:211], v[96:99], v[188:191], v[196:211]
	v_mfma_f32_32x32x16_bf16 v[236:251], v[96:99], v[192:195], v[236:251]
	s_waitcnt lgkmcnt(0)
	s_barrier
	s_mov_b32 m0, s6
	v_lshl_add_u64 v[82:83], v[66:67], 0, s[26:27]
	v_mfma_f32_32x32x16_bf16 v[104:119], v[100:103], v[212:215], v[104:119]
	global_load_lds_dwordx4 v[82:83], off
	v_lshl_add_u64 v[66:67], v[66:67], 0, s[34:35]
	v_mfma_f32_32x32x16_bf16 v[128:143], v[100:103], v[216:219], v[128:143]
	s_mov_b32 m0, s13
	v_lshl_add_u64 v[82:83], v[70:71], 0, s[26:27]
	v_mfma_f32_32x32x16_bf16 v[196:211], v[144:147], v[212:215], v[196:211]
	global_load_lds_dwordx4 v[82:83], off
	v_lshl_add_u64 v[70:71], v[70:71], 0, s[34:35]
	v_mfma_f32_32x32x16_bf16 v[236:251], v[144:147], v[216:219], v[236:251]
	s_mov_b32 m0, s15
	v_lshl_add_u64 v[82:83], v[74:75], 0, s[26:27]
	v_mfma_f32_32x32x16_bf16 v[104:119], v[148:151], v[220:223], v[104:119]
	global_load_lds_dwordx4 v[82:83], off
	v_lshl_add_u64 v[74:75], v[74:75], 0, s[34:35]
	v_mfma_f32_32x32x16_bf16 v[128:143], v[148:151], v[224:227], v[128:143]
	s_mov_b32 m0, s17
	v_lshl_add_u64 v[82:83], v[78:79], 0, s[26:27]
	v_mfma_f32_32x32x16_bf16 v[196:211], v[152:155], v[220:223], v[196:211]
	global_load_lds_dwordx4 v[82:83], off
	v_lshl_add_u64 v[78:79], v[78:79], 0, s[34:35]
	v_mfma_f32_32x32x16_bf16 v[236:251], v[152:155], v[224:227], v[236:251]
	s_mov_b32 m0, s16
	v_mfma_f32_32x32x16_bf16 v[104:119], v[180:183], v[228:231], v[104:119]
	global_load_lds_dwordx4 v[76:77], off
	v_lshl_add_u64 v[76:77], v[76:77], 0, s[34:35]
	v_mfma_f32_32x32x16_bf16 v[128:143], v[180:183], v[252:255], v[128:143]
	s_mov_b32 m0, s25
	v_mfma_f32_32x32x16_bf16 v[196:211], v[184:187], v[228:231], v[196:211]
	global_load_lds_dwordx4 v[80:81], off
	v_lshl_add_u64 v[80:81], v[80:81], 0, s[34:35]
	v_mfma_f32_32x32x16_bf16 v[236:251], v[184:187], v[252:255], v[236:251]
	s_waitcnt vmcnt(8)
	s_barrier
	s_add_i32 s12, s12, 2
	s_cmp_lt_u32 s12, 14
	s_cbranch_scc1 .Lg1_loop_w1
	ds_read_b128 v[92:95], v84 offset:0
	ds_read_b128 v[96:99], v84 offset:4096
	ds_read_b128 v[188:191], v85 offset:0
	ds_read_b128 v[192:195], v85 offset:4096
	ds_read_b128 v[100:103], v86 offset:0
	ds_read_b128 v[144:147], v86 offset:4096
	ds_read_b128 v[212:215], v87 offset:0
	ds_read_b128 v[216:219], v87 offset:4096
	ds_read_b128 v[148:151], v88 offset:0
	ds_read_b128 v[152:155], v88 offset:4096
	ds_read_b128 v[220:223], v89 offset:0
	ds_read_b128 v[224:227], v89 offset:4096
	ds_read_b128 v[180:183], v90 offset:0
	ds_read_b128 v[184:187], v90 offset:4096
	ds_read_b128 v[228:231], v91 offset:0
	ds_read_b128 v[252:255], v91 offset:4096
	s_waitcnt lgkmcnt(12)
	v_mfma_f32_32x32x16_bf16 v[18:33], v[92:95], v[188:191], v[18:33]
	v_mfma_f32_32x32x16_bf16 v[50:65], v[92:95], v[192:195], v[50:65]
	v_mfma_f32_32x32x16_bf16 v[2:17], v[96:99], v[188:191], v[2:17]
	v_mfma_f32_32x32x16_bf16 v[34:49], v[96:99], v[192:195], v[34:49]
	s_waitcnt lgkmcnt(0)
	s_barrier
	s_mov_b32 m0, s1
	v_mfma_f32_32x32x16_bf16 v[18:33], v[100:103], v[212:215], v[18:33]
	global_load_lds_dwordx4 v[66:67], off
	v_mfma_f32_32x32x16_bf16 v[50:65], v[100:103], v[216:219], v[50:65]
	s_add_i32 m0, s1, 0x400
	v_mfma_f32_32x32x16_bf16 v[2:17], v[144:147], v[212:215], v[2:17]
	global_load_lds_dwordx4 v[70:71], off
	v_mfma_f32_32x32x16_bf16 v[34:49], v[144:147], v[216:219], v[34:49]
	v_mfma_f32_32x32x16_bf16 v[18:33], v[148:151], v[220:223], v[18:33]
	v_mfma_f32_32x32x16_bf16 v[50:65], v[148:151], v[224:227], v[50:65]
	s_add_i32 m0, s1, 0x800
	v_mfma_f32_32x32x16_bf16 v[2:17], v[152:155], v[220:223], v[2:17]
	global_load_lds_dwordx4 v[74:75], off
	v_mfma_f32_32x32x16_bf16 v[34:49], v[152:155], v[224:227], v[34:49]
	s_add_i32 m0, s1, 0xc00
	v_mfma_f32_32x32x16_bf16 v[18:33], v[180:183], v[228:231], v[18:33]
	global_load_lds_dwordx4 v[78:79], off
	v_mfma_f32_32x32x16_bf16 v[50:65], v[180:183], v[252:255], v[50:65]
	v_mfma_f32_32x32x16_bf16 v[2:17], v[184:187], v[228:231], v[2:17]
	v_mfma_f32_32x32x16_bf16 v[34:49], v[184:187], v[252:255], v[34:49]
	s_waitcnt vmcnt(4)
	s_barrier
	ds_read_b128 v[92:95], v84 offset:32768
	ds_read_b128 v[96:99], v84 offset:36864
	ds_read_b128 v[100:103], v86 offset:32768
	ds_read_b128 v[144:147], v86 offset:36864
	ds_read_b128 v[148:151], v88 offset:32768
	ds_read_b128 v[152:155], v88 offset:36864
	ds_read_b128 v[180:183], v90 offset:32768
	ds_read_b128 v[184:187], v90 offset:36864
	s_waitcnt lgkmcnt(6)
	v_mfma_f32_32x32x16_bf16 v[104:119], v[92:95], v[188:191], v[104:119]
	v_mfma_f32_32x32x16_bf16 v[128:143], v[92:95], v[192:195], v[128:143]
	v_mfma_f32_32x32x16_bf16 v[196:211], v[96:99], v[188:191], v[196:211]
	v_mfma_f32_32x32x16_bf16 v[236:251], v[96:99], v[192:195], v[236:251]
	s_waitcnt lgkmcnt(0)
	s_barrier
	s_mov_b32 m0, s6
	v_lshl_add_u64 v[82:83], v[66:67], 0, s[26:27]
	v_mfma_f32_32x32x16_bf16 v[104:119], v[100:103], v[212:215], v[104:119]
	global_load_lds_dwordx4 v[82:83], off
	v_lshl_add_u64 v[66:67], v[66:67], 0, s[34:35]
	v_mfma_f32_32x32x16_bf16 v[128:143], v[100:103], v[216:219], v[128:143]
	s_mov_b32 m0, s13
	v_lshl_add_u64 v[82:83], v[70:71], 0, s[26:27]
	v_mfma_f32_32x32x16_bf16 v[196:211], v[144:147], v[212:215], v[196:211]
	global_load_lds_dwordx4 v[82:83], off
	v_lshl_add_u64 v[70:71], v[70:71], 0, s[34:35]
	v_mfma_f32_32x32x16_bf16 v[236:251], v[144:147], v[216:219], v[236:251]
	v_mfma_f32_32x32x16_bf16 v[104:119], v[148:151], v[220:223], v[104:119]
	v_mfma_f32_32x32x16_bf16 v[128:143], v[148:151], v[224:227], v[128:143]
	s_mov_b32 m0, s15
	v_lshl_add_u64 v[82:83], v[74:75], 0, s[26:27]
	v_mfma_f32_32x32x16_bf16 v[196:211], v[152:155], v[220:223], v[196:211]
	global_load_lds_dwordx4 v[82:83], off
	v_lshl_add_u64 v[74:75], v[74:75], 0, s[34:35]
	v_mfma_f32_32x32x16_bf16 v[236:251], v[152:155], v[224:227], v[236:251]
	s_mov_b32 m0, s17
	v_lshl_add_u64 v[82:83], v[78:79], 0, s[26:27]
	v_mfma_f32_32x32x16_bf16 v[104:119], v[180:183], v[228:231], v[104:119]
	global_load_lds_dwordx4 v[82:83], off
	v_lshl_add_u64 v[78:79], v[78:79], 0, s[34:35]
	v_mfma_f32_32x32x16_bf16 v[128:143], v[180:183], v[252:255], v[128:143]
	v_mfma_f32_32x32x16_bf16 v[196:211], v[184:187], v[228:231], v[196:211]
	v_mfma_f32_32x32x16_bf16 v[236:251], v[184:187], v[252:255], v[236:251]
	s_waitcnt vmcnt(4)
	s_barrier
	ds_read_b128 v[92:95], v84 offset:0
	ds_read_b128 v[96:99], v84 offset:4096
	ds_read_b128 v[188:191], v85 offset:32768
	ds_read_b128 v[192:195], v85 offset:36864
	ds_read_b128 v[100:103], v86 offset:0
	ds_read_b128 v[144:147], v86 offset:4096
	ds_read_b128 v[212:215], v87 offset:32768
	ds_read_b128 v[216:219], v87 offset:36864
	ds_read_b128 v[148:151], v88 offset:0
	ds_read_b128 v[152:155], v88 offset:4096
	ds_read_b128 v[220:223], v89 offset:32768
	ds_read_b128 v[224:227], v89 offset:36864
	ds_read_b128 v[180:183], v90 offset:0
	ds_read_b128 v[184:187], v90 offset:4096
	ds_read_b128 v[228:231], v91 offset:32768
	ds_read_b128 v[252:255], v91 offset:36864
	s_waitcnt lgkmcnt(12)
	v_mfma_f32_32x32x16_bf16 v[18:33], v[92:95], v[188:191], v[18:33]
	v_mfma_f32_32x32x16_bf16 v[50:65], v[92:95], v[192:195], v[50:65]
	v_mfma_f32_32x32x16_bf16 v[2:17], v[96:99], v[188:191], v[2:17]
	v_mfma_f32_32x32x16_bf16 v[34:49], v[96:99], v[192:195], v[34:49]
	s_waitcnt lgkmcnt(0)
	s_barrier
	v_mfma_f32_32x32x16_bf16 v[18:33], v[100:103], v[212:215], v[18:33]
	v_mfma_f32_32x32x16_bf16 v[50:65], v[100:103], v[216:219], v[50:65]
	v_mfma_f32_32x32x16_bf16 v[2:17], v[144:147], v[212:215], v[2:17]
	v_mfma_f32_32x32x16_bf16 v[34:49], v[144:147], v[216:219], v[34:49]
	v_mfma_f32_32x32x16_bf16 v[18:33], v[148:151], v[220:223], v[18:33]
	v_mfma_f32_32x32x16_bf16 v[50:65], v[148:151], v[224:227], v[50:65]
	v_mfma_f32_32x32x16_bf16 v[2:17], v[152:155], v[220:223], v[2:17]
	v_mfma_f32_32x32x16_bf16 v[34:49], v[152:155], v[224:227], v[34:49]
	v_mfma_f32_32x32x16_bf16 v[18:33], v[180:183], v[228:231], v[18:33]
	v_mfma_f32_32x32x16_bf16 v[50:65], v[180:183], v[252:255], v[50:65]
	v_mfma_f32_32x32x16_bf16 v[2:17], v[184:187], v[228:231], v[2:17]
	v_mfma_f32_32x32x16_bf16 v[34:49], v[184:187], v[252:255], v[34:49]
	s_waitcnt vmcnt(0)
	s_barrier
	ds_read_b128 v[92:95], v84 offset:32768
	ds_read_b128 v[96:99], v84 offset:36864
	ds_read_b128 v[100:103], v86 offset:32768
	ds_read_b128 v[144:147], v86 offset:36864
	ds_read_b128 v[148:151], v88 offset:32768
	ds_read_b128 v[152:155], v88 offset:36864
	ds_read_b128 v[180:183], v90 offset:32768
	ds_read_b128 v[184:187], v90 offset:36864
	s_waitcnt lgkmcnt(6)
	v_mfma_f32_32x32x16_bf16 v[104:119], v[92:95], v[188:191], v[104:119]
	v_mfma_f32_32x32x16_bf16 v[128:143], v[92:95], v[192:195], v[128:143]
	v_mfma_f32_32x32x16_bf16 v[196:211], v[96:99], v[188:191], v[196:211]
	v_mfma_f32_32x32x16_bf16 v[236:251], v[96:99], v[192:195], v[236:251]
	s_waitcnt lgkmcnt(0)
	s_barrier
	v_mfma_f32_32x32x16_bf16 v[104:119], v[100:103], v[212:215], v[104:119]
	v_mfma_f32_32x32x16_bf16 v[128:143], v[100:103], v[216:219], v[128:143]
	v_mfma_f32_32x32x16_bf16 v[196:211], v[144:147], v[212:215], v[196:211]
	v_mfma_f32_32x32x16_bf16 v[236:251], v[144:147], v[216:219], v[236:251]
	v_mfma_f32_32x32x16_bf16 v[104:119], v[148:151], v[220:223], v[104:119]
	v_mfma_f32_32x32x16_bf16 v[128:143], v[148:151], v[224:227], v[128:143]
	v_mfma_f32_32x32x16_bf16 v[196:211], v[152:155], v[220:223], v[196:211]
	v_mfma_f32_32x32x16_bf16 v[236:251], v[152:155], v[224:227], v[236:251]
	v_mfma_f32_32x32x16_bf16 v[104:119], v[180:183], v[228:231], v[104:119]
	v_mfma_f32_32x32x16_bf16 v[128:143], v[180:183], v[252:255], v[128:143]
	v_mfma_f32_32x32x16_bf16 v[196:211], v[184:187], v[228:231], v[196:211]
	v_mfma_f32_32x32x16_bf16 v[236:251], v[184:187], v[252:255], v[236:251]
	s_waitcnt vmcnt(0) lgkmcnt(0)
	s_barrier
	s_branch .LBB0_187
.Lg1_loop_w2:
	ds_read_b128 v[92:95], v84 offset:0
	ds_read_b128 v[96:99], v84 offset:4096
	ds_read_b128 v[188:191], v85 offset:0
	ds_read_b128 v[192:195], v85 offset:4096
	ds_read_b128 v[100:103], v86 offset:0
	ds_read_b128 v[144:147], v86 offset:4096
	ds_read_b128 v[212:215], v87 offset:0
	ds_read_b128 v[216:219], v87 offset:4096
	ds_read_b128 v[148:151], v88 offset:0
	ds_read_b128 v[152:155], v88 offset:4096
	ds_read_b128 v[220:223], v89 offset:0
	ds_read_b128 v[224:227], v89 offset:4096
	ds_read_b128 v[180:183], v90 offset:0
	ds_read_b128 v[184:187], v90 offset:4096
	ds_read_b128 v[228:231], v91 offset:0
	ds_read_b128 v[252:255], v91 offset:4096
	s_waitcnt lgkmcnt(12)
	v_mfma_f32_32x32x16_bf16 v[18:33], v[92:95], v[188:191], v[18:33]
	v_mfma_f32_32x32x16_bf16 v[50:65], v[92:95], v[192:195], v[50:65]
	v_mfma_f32_32x32x16_bf16 v[2:17], v[96:99], v[188:191], v[2:17]
	v_mfma_f32_32x32x16_bf16 v[34:49], v[96:99], v[192:195], v[34:49]
	s_waitcnt lgkmcnt(0)
	s_barrier
	s_mov_b32 m0, s1
	v_mfma_f32_32x32x16_bf16 v[18:33], v[100:103], v[212:215], v[18:33]
	global_load_lds_dwordx4 v[66:67], off
	v_mfma_f32_32x32x16_bf16 v[50:65], v[100:103], v[216:219], v[50:65]
	s_add_i32 m0, s1, 0x400
	v_mfma_f32_32x32x16_bf16 v[2:17], v[144:147], v[212:215], v[2:17]
	global_load_lds_dwordx4 v[70:71], off
	v_mfma_f32_32x32x16_bf16 v[34:49], v[144:147], v[216:219], v[34:49]
	v_mfma_f32_32x32x16_bf16 v[18:33], v[148:151], v[220:223], v[18:33]
	s_add_i32 m0, s1, 0x800
	v_mfma_f32_32x32x16_bf16 v[50:65], v[148:151], v[224:227], v[50:65]
	global_load_lds_dwordx4 v[74:75], off
	s_add_i32 m0, s1, 0xc00
	v_mfma_f32_32x32x16_bf16 v[2:17], v[152:155], v[220:223], v[2:17]
	global_load_lds_dwordx4 v[78:79], off
	v_mfma_f32_32x32x16_bf16 v[34:49], v[152:155], v[224:227], v[34:49]
	s_mov_b32 m0, s8
	v_mfma_f32_32x32x16_bf16 v[18:33], v[180:183], v[228:231], v[18:33]
	global_load_lds_dwordx4 v[68:69], off
	v_lshl_add_u64 v[68:69], v[68:69], 0, s[34:35]
	v_mfma_f32_32x32x16_bf16 v[50:65], v[180:183], v[252:255], v[50:65]
	v_mfma_f32_32x32x16_bf16 v[2:17], v[184:187], v[228:231], v[2:17]
	s_mov_b32 m0, s9
	v_mfma_f32_32x32x16_bf16 v[34:49], v[184:187], v[252:255], v[34:49]
	global_load_lds_dwordx4 v[72:73], off
	v_lshl_add_u64 v[72:73], v[72:73], 0, s[34:35]
	s_waitcnt vmcnt(8)
	s_barrier
	ds_read_b128 v[92:95], v84 offset:32768
	ds_read_b128 v[96:99], v84 offset:36864
	ds_read_b128 v[100:103], v86 offset:32768
	ds_read_b128 v[144:147], v86 offset:36864
	ds_read_b128 v[148:151], v88 offset:32768
	ds_read_b128 v[152:155], v88 offset:36864
	ds_read_b128 v[180:183], v90 offset:32768
	ds_read_b128 v[184:187], v90 offset:36864
	s_waitcnt lgkmcnt(6)
	v_mfma_f32_32x32x16_bf16 v[104:119], v[92:95], v[188:191], v[104:119]
	v_mfma_f32_32x32x16_bf16 v[128:143], v[92:95], v[192:195], v[128:143]
	v_mfma_f32_32x32x16_bf16 v[196:211], v[96:99], v[188:191], v[196:211]
	v_mfma_f32_32x32x16_bf16 v[236:251], v[96:99], v[192:195], v[236:251]
	s_waitcnt lgkmcnt(0)
	s_barrier
	s_mov_b32 m0, s6
	v_lshl_add_u64 v[82:83], v[66:67], 0, s[26:27]
	v_mfma_f32_32x32x16_bf16 v[104:119], v[100:103], v[212:215], v[104:119]
	global_load_lds_dwordx4 v[82:83], off
	v_lshl_add_u64 v[66:67], v[66:67], 0, s[34:35]
	v_mfma_f32_32x32x16_bf16 v[128:143], v[100:103], v[216:219], v[128:143]
	s_mov_b32 m0, s13
	v_lshl_add_u64 v[82:83], v[70:71], 0, s[26:27]
	v_mfma_f32_32x32x16_bf16 v[196:211], v[144:147], v[212:215], v[196:211]
	global_load_lds_dwordx4 v[82:83], off
	v_lshl_add_u64 v[70:71], v[70:71], 0, s[34:35]
	v_mfma_f32_32x32x16_bf16 v[236:251], v[144:147], v[216:219], v[236:251]
	v_mfma_f32_32x32x16_bf16 v[104:119], v[148:151], v[220:223], v[104:119]
	s_mov_b32 m0, s15
	v_lshl_add_u64 v[82:83], v[74:75], 0, s[26:27]
	v_mfma_f32_32x32x16_bf16 v[128:143], v[148:151], v[224:227], v[128:143]
	global_load_lds_dwordx4 v[82:83], off
	v_lshl_add_u64 v[74:75], v[74:75], 0, s[34:35]
	s_mov_b32 m0, s17
	v_lshl_add_u64 v[82:83], v[78:79], 0, s[26:27]
	v_mfma_f32_32x32x16_bf16 v[196:211], v[152:155], v[220:223], v[196:211]
	global_load_lds_dwordx4 v[82:83], off
	v_lshl_add_u64 v[78:79], v[78:79], 0, s[34:35]
	v_mfma_f32_32x32x16_bf16 v[236:251], v[152:155], v[224:227], v[236:251]
	s_mov_b32 m0, s10
	v_mfma_f32_32x32x16_bf16 v[104:119], v[180:183], v[228:231], v[104:119]
	global_load_lds_dwordx4 v[76:77], off
	v_lshl_add_u64 v[76:77], v[76:77], 0, s[34:35]
	v_mfma_f32_32x32x16_bf16 v[128:143], v[180:183], v[252:255], v[128:143]
	v_mfma_f32_32x32x16_bf16 v[196:211], v[184:187], v[228:231], v[196:211]
	s_mov_b32 m0, s11
	v_mfma_f32_32x32x16_bf16 v[236:251], v[184:187], v[252:255], v[236:251]
	global_load_lds_dwordx4 v[80:81], off
	v_lshl_add_u64 v[80:81], v[80:81], 0, s[34:35]
	s_waitcnt vmcnt(8)
	s_barrier
	ds_read_b128 v[92:95], v84 offset:0
	ds_read_b128 v[96:99], v84 offset:4096
	ds_read_b128 v[188:191], v85 offset:32768
	ds_read_b128 v[192:195], v85 offset:36864
	ds_read_b128 v[100:103], v86 offset:0
	ds_read_b128 v[144:147], v86 offset:4096
	ds_read_b128 v[212:215], v87 offset:32768
	ds_read_b128 v[216:219], v87 offset:36864
	ds_read_b128 v[148:151], v88 offset:0
	ds_read_b128 v[152:155], v88 offset:4096
	ds_read_b128 v[220:223], v89 offset:32768
	ds_read_b128 v[224:227], v89 offset:36864
	ds_read_b128 v[180:183], v90 offset:0
	ds_read_b128 v[184:187], v90 offset:4096
	ds_read_b128 v[228:231], v91 offset:32768
	ds_read_b128 v[252:255], v91 offset:36864
	s_waitcnt lgkmcnt(12)
	v_mfma_f32_32x32x16_bf16 v[18:33], v[92:95], v[188:191], v[18:33]
	v_mfma_f32_32x32x16_bf16 v[50:65], v[92:95], v[192:195], v[50:65]
	v_mfma_f32_32x32x16_bf16 v[2:17], v[96:99], v[188:191], v[2:17]
	v_mfma_f32_32x32x16_bf16 v[34:49], v[96:99], v[192:195], v[34:49]
	s_waitcnt lgkmcnt(0)
	s_barrier
	s_mov_b32 m0, s1
	v_mfma_f32_32x32x16_bf16 v[18:33], v[100:103], v[212:215], v[18:33]
	global_load_lds_dwordx4 v[66:67], off
	v_mfma_f32_32x32x16_bf16 v[50:65], v[100:103], v[216:219], v[50:65]
	s_add_i32 m0, s1, 0x400
	v_mfma_f32_32x32x16_bf16 v[2:17], v[144:147], v[212:215], v[2:17]
	global_load_lds_dwordx4 v[70:71], off
	v_mfma_f32_32x32x16_bf16 v[34:49], v[144:147], v[216:219], v[34:49]
	v_mfma_f32_32x32x16_bf16 v[18:33], v[148:151], v[220:223], v[18:33]
	s_add_i32 m0, s1, 0x800
	v_mfma_f32_32x32x16_bf16 v[50:65], v[148:151], v[224:227], v[50:65]
	global_load_lds_dwordx4 v[74:75], off
	s_add_i32 m0, s1, 0xc00
	v_mfma_f32_32x32x16_bf16 v[2:17], v[152:155], v[220:223], v[2:17]
	global_load_lds_dwordx4 v[78:79], off
	v_mfma_f32_32x32x16_bf16 v[34:49], v[152:155], v[224:227], v[34:49]
	s_mov_b32 m0, s7
	v_mfma_f32_32x32x16_bf16 v[18:33], v[180:183], v[228:231], v[18:33]
	global_load_lds_dwordx4 v[68:69], off
	v_lshl_add_u64 v[68:69], v[68:69], 0, s[34:35]
	v_mfma_f32_32x32x16_bf16 v[50:65], v[180:183], v[252:255], v[50:65]
	v_mfma_f32_32x32x16_bf16 v[2:17], v[184:187], v[228:231], v[2:17]
	s_mov_b32 m0, s14
	v_mfma_f32_32x32x16_bf16 v[34:49], v[184:187], v[252:255], v[34:49]
	global_load_lds_dwordx4 v[72:73], off
	v_lshl_add_u64 v[72:73], v[72:73], 0, s[34:35]
	s_waitcnt vmcnt(8)
	s_barrier
	ds_read_b128 v[92:95], v84 offset:32768
	ds_read_b128 v[96:99], v84 offset:36864
	ds_read_b128 v[100:103], v86 offset:32768
	ds_read_b128 v[144:147], v86 offset:36864
	ds_read_b128 v[148:151], v88 offset:32768
	ds_read_b128 v[152:155], v88 offset:36864
	ds_read_b128 v[180:183], v90 offset:32768
	ds_read_b128 v[184:187], v90 offset:36864
	s_waitcnt lgkmcnt(6)
	v_mfma_f32_32x32x16_bf16 v[104:119], v[92:95], v[188:191], v[104:119]
	v_mfma_f32_32x32x16_bf16 v[128:143], v[92:95], v[192:195], v[128:143]
	v_mfma_f32_32x32x16_bf16 v[196:211], v[96:99], v[188:191], v[196:211]
	v_mfma_f32_32x32x16_bf16 v[236:251], v[96:99], v[192:195], v[236:251]
	s_waitcnt lgkmcnt(0)
	s_barrier
	s_mov_b32 m0, s6
	v_lshl_add_u64 v[82:83], v[66:67], 0, s[26:27]
	v_mfma_f32_32x32x16_bf16 v[104:119], v[100:103], v[212:215], v[104:119]
	global_load_lds_dwordx4 v[82:83], off
	v_lshl_add_u64 v[66:67], v[66:67], 0, s[34:35]
	v_mfma_f32_32x32x16_bf16 v[128:143], v[100:103], v[216:219], v[128:143]
	s_mov_b32 m0, s13
	v_lshl_add_u64 v[82:83], v[70:71], 0, s[26:27]
	v_mfma_f32_32x32x16_bf16 v[196:211], v[144:147], v[212:215], v[196:211]
	global_load_lds_dwordx4 v[82:83], off
	v_lshl_add_u64 v[70:71], v[70:71], 0, s[34:35]
	v_mfma_f32_32x32x16_bf16 v[236:251], v[144:147], v[216:219], v[236:251]
	v_mfma_f32_32x32x16_bf16 v[104:119], v[148:151], v[220:223], v[104:119]
	s_mov_b32 m0, s15
	v_lshl_add_u64 v[82:83], v[74:75], 0, s[26:27]
	v_mfma_f32_32x32x16_bf16 v[128:143], v[148:151], v[224:227], v[128:143]
	global_load_lds_dwordx4 v[82:83], off
	v_lshl_add_u64 v[74:75], v[74:75], 0, s[34:35]
	s_mov_b32 m0, s17
	v_lshl_add_u64 v[82:83], v[78:79], 0, s[26:27]
	v_mfma_f32_32x32x16_bf16 v[196:211], v[152:155], v[220:223], v[196:211]
	global_load_lds_dwordx4 v[82:83], off
	v_lshl_add_u64 v[78:79], v[78:79], 0, s[34:35]
	v_mfma_f32_32x32x16_bf16 v[236:251], v[152:155], v[224:227], v[236:251]
	s_mov_b32 m0, s16
	v_mfma_f32_32x32x16_bf16 v[104:119], v[180:183], v[228:231], v[104:119]
	global_load_lds_dwordx4 v[76:77], off
	v_lshl_add_u64 v[76:77], v[76:77], 0, s[34:35]
	v_mfma_f32_32x32x16_bf16 v[128:143], v[180:183], v[252:255], v[128:143]
	v_mfma_f32_32x32x16_bf16 v[196:211], v[184:187], v[228:231], v[196:211]
	s_mov_b32 m0, s25
	v_mfma_f32_32x32x16_bf16 v[236:251], v[184:187], v[252:255], v[236:251]
	global_load_lds_dwordx4 v[80:81], off
	v_lshl_add_u64 v[80:81], v[80:81], 0, s[34:35]
	s_waitcnt vmcnt(8)
	s_barrier
	s_add_i32 s12, s12, 2
	s_cmp_lt_u32 s12, 14
	s_cbranch_scc1 .Lg1_loop_w2
	ds_read_b128 v[92:95], v84 offset:0
	ds_read_b128 v[96:99], v84 offset:4096
	ds_read_b128 v[188:191], v85 offset:0
	ds_read_b128 v[192:195], v85 offset:4096
	ds_read_b128 v[100:103], v86 offset:0
	ds_read_b128 v[144:147], v86 offset:4096
	ds_read_b128 v[212:215], v87 offset:0
	ds_read_b128 v[216:219], v87 offset:4096
	ds_read_b128 v[148:151], v88 offset:0
	ds_read_b128 v[152:155], v88 offset:4096
	ds_read_b128 v[220:223], v89 offset:0
	ds_read_b128 v[224:227], v89 offset:4096
	ds_read_b128 v[180:183], v90 offset:0
	ds_read_b128 v[184:187], v90 offset:4096
	ds_read_b128 v[228:231], v91 offset:0
	ds_read_b128 v[252:255], v91 offset:4096
	s_waitcnt lgkmcnt(12)
	v_mfma_f32_32x32x16_bf16 v[18:33], v[92:95], v[188:191], v[18:33]
	v_mfma_f32_32x32x16_bf16 v[50:65], v[92:95], v[192:195], v[50:65]
	v_mfma_f32_32x32x16_bf16 v[2:17], v[96:99], v[188:191], v[2:17]
	v_mfma_f32_32x32x16_bf16 v[34:49], v[96:99], v[192:195], v[34:49]
	s_waitcnt lgkmcnt(0)
	s_barrier
	s_mov_b32 m0, s1
	v_mfma_f32_32x32x16_bf16 v[18:33], v[100:103], v[212:215], v[18:33]
	global_load_lds_dwordx4 v[66:67], off
	v_mfma_f32_32x32x16_bf16 v[50:65], v[100:103], v[216:219], v[50:65]
	s_add_i32 m0, s1, 0x400
	v_mfma_f32_32x32x16_bf16 v[2:17], v[144:147], v[212:215], v[2:17]
	global_load_lds_dwordx4 v[70:71], off
	v_mfma_f32_32x32x16_bf16 v[34:49], v[144:147], v[216:219], v[34:49]
	v_mfma_f32_32x32x16_bf16 v[18:33], v[148:151], v[220:223], v[18:33]
	v_mfma_f32_32x32x16_bf16 v[50:65], v[148:151], v[224:227], v[50:65]
	s_add_i32 m0, s1, 0x800
	v_mfma_f32_32x32x16_bf16 v[2:17], v[152:155], v[220:223], v[2:17]
	global_load_lds_dwordx4 v[74:75], off
	v_mfma_f32_32x32x16_bf16 v[34:49], v[152:155], v[224:227], v[34:49]
	s_add_i32 m0, s1, 0xc00
	v_mfma_f32_32x32x16_bf16 v[18:33], v[180:183], v[228:231], v[18:33]
	global_load_lds_dwordx4 v[78:79], off
	v_mfma_f32_32x32x16_bf16 v[50:65], v[180:183], v[252:255], v[50:65]
	v_mfma_f32_32x32x16_bf16 v[2:17], v[184:187], v[228:231], v[2:17]
	v_mfma_f32_32x32x16_bf16 v[34:49], v[184:187], v[252:255], v[34:49]
	s_waitcnt vmcnt(4)
	s_barrier
	ds_read_b128 v[92:95], v84 offset:32768
	ds_read_b128 v[96:99], v84 offset:36864
	ds_read_b128 v[100:103], v86 offset:32768
	ds_read_b128 v[144:147], v86 offset:36864
	ds_read_b128 v[148:151], v88 offset:32768
	ds_read_b128 v[152:155], v88 offset:36864
	ds_read_b128 v[180:183], v90 offset:32768
	ds_read_b128 v[184:187], v90 offset:36864
	s_waitcnt lgkmcnt(6)
	v_mfma_f32_32x32x16_bf16 v[104:119], v[92:95], v[188:191], v[104:119]
	v_mfma_f32_32x32x16_bf16 v[128:143], v[92:95], v[192:195], v[128:143]
	v_mfma_f32_32x32x16_bf16 v[196:211], v[96:99], v[188:191], v[196:211]
	v_mfma_f32_32x32x16_bf16 v[236:251], v[96:99], v[192:195], v[236:251]
	s_waitcnt lgkmcnt(0)
	s_barrier
	s_mov_b32 m0, s6
	v_lshl_add_u64 v[82:83], v[66:67], 0, s[26:27]
	v_mfma_f32_32x32x16_bf16 v[104:119], v[100:103], v[212:215], v[104:119]
	global_load_lds_dwordx4 v[82:83], off
	v_lshl_add_u64 v[66:67], v[66:67], 0, s[34:35]
	v_mfma_f32_32x32x16_bf16 v[128:143], v[100:103], v[216:219], v[128:143]
	s_mov_b32 m0, s13
	v_lshl_add_u64 v[82:83], v[70:71], 0, s[26:27]
	v_mfma_f32_32x32x16_bf16 v[196:211], v[144:147], v[212:215], v[196:211]
	global_load_lds_dwordx4 v[82:83], off
	v_lshl_add_u64 v[70:71], v[70:71], 0, s[34:35]
	v_mfma_f32_32x32x16_bf16 v[236:251], v[144:147], v[216:219], v[236:251]
	v_mfma_f32_32x32x16_bf16 v[104:119], v[148:151], v[220:223], v[104:119]
	v_mfma_f32_32x32x16_bf16 v[128:143], v[148:151], v[224:227], v[128:143]
	s_mov_b32 m0, s15
	v_lshl_add_u64 v[82:83], v[74:75], 0, s[26:27]
	v_mfma_f32_32x32x16_bf16 v[196:211], v[152:155], v[220:223], v[196:211]
	global_load_lds_dwordx4 v[82:83], off
	v_lshl_add_u64 v[74:75], v[74:75], 0, s[34:35]
	v_mfma_f32_32x32x16_bf16 v[236:251], v[152:155], v[224:227], v[236:251]
	s_mov_b32 m0, s17
	v_lshl_add_u64 v[82:83], v[78:79], 0, s[26:27]
	v_mfma_f32_32x32x16_bf16 v[104:119], v[180:183], v[228:231], v[104:119]
	global_load_lds_dwordx4 v[82:83], off
	v_lshl_add_u64 v[78:79], v[78:79], 0, s[34:35]
	v_mfma_f32_32x32x16_bf16 v[128:143], v[180:183], v[252:255], v[128:143]
	v_mfma_f32_32x32x16_bf16 v[196:211], v[184:187], v[228:231], v[196:211]
	v_mfma_f32_32x32x16_bf16 v[236:251], v[184:187], v[252:255], v[236:251]
	s_waitcnt vmcnt(4)
	s_barrier
	ds_read_b128 v[92:95], v84 offset:0
	ds_read_b128 v[96:99], v84 offset:4096
	ds_read_b128 v[188:191], v85 offset:32768
	ds_read_b128 v[192:195], v85 offset:36864
	ds_read_b128 v[100:103], v86 offset:0
	ds_read_b128 v[144:147], v86 offset:4096
	ds_read_b128 v[212:215], v87 offset:32768
	ds_read_b128 v[216:219], v87 offset:36864
	ds_read_b128 v[148:151], v88 offset:0
	ds_read_b128 v[152:155], v88 offset:4096
	ds_read_b128 v[220:223], v89 offset:32768
	ds_read_b128 v[224:227], v89 offset:36864
	ds_read_b128 v[180:183], v90 offset:0
	ds_read_b128 v[184:187], v90 offset:4096
	ds_read_b128 v[228:231], v91 offset:32768
	ds_read_b128 v[252:255], v91 offset:36864
	s_waitcnt lgkmcnt(12)
	v_mfma_f32_32x32x16_bf16 v[18:33], v[92:95], v[188:191], v[18:33]
	v_mfma_f32_32x32x16_bf16 v[50:65], v[92:95], v[192:195], v[50:65]
	v_mfma_f32_32x32x16_bf16 v[2:17], v[96:99], v[188:191], v[2:17]
	v_mfma_f32_32x32x16_bf16 v[34:49], v[96:99], v[192:195], v[34:49]
	s_waitcnt lgkmcnt(0)
	s_barrier
	v_mfma_f32_32x32x16_bf16 v[18:33], v[100:103], v[212:215], v[18:33]
	v_mfma_f32_32x32x16_bf16 v[50:65], v[100:103], v[216:219], v[50:65]
	v_mfma_f32_32x32x16_bf16 v[2:17], v[144:147], v[212:215], v[2:17]
	v_mfma_f32_32x32x16_bf16 v[34:49], v[144:147], v[216:219], v[34:49]
	v_mfma_f32_32x32x16_bf16 v[18:33], v[148:151], v[220:223], v[18:33]
	v_mfma_f32_32x32x16_bf16 v[50:65], v[148:151], v[224:227], v[50:65]
	v_mfma_f32_32x32x16_bf16 v[2:17], v[152:155], v[220:223], v[2:17]
	v_mfma_f32_32x32x16_bf16 v[34:49], v[152:155], v[224:227], v[34:49]
	v_mfma_f32_32x32x16_bf16 v[18:33], v[180:183], v[228:231], v[18:33]
	v_mfma_f32_32x32x16_bf16 v[50:65], v[180:183], v[252:255], v[50:65]
	v_mfma_f32_32x32x16_bf16 v[2:17], v[184:187], v[228:231], v[2:17]
	v_mfma_f32_32x32x16_bf16 v[34:49], v[184:187], v[252:255], v[34:49]
	s_waitcnt vmcnt(0)
	s_barrier
	ds_read_b128 v[92:95], v84 offset:32768
	ds_read_b128 v[96:99], v84 offset:36864
	ds_read_b128 v[100:103], v86 offset:32768
	ds_read_b128 v[144:147], v86 offset:36864
	ds_read_b128 v[148:151], v88 offset:32768
	ds_read_b128 v[152:155], v88 offset:36864
	ds_read_b128 v[180:183], v90 offset:32768
	ds_read_b128 v[184:187], v90 offset:36864
	s_waitcnt lgkmcnt(6)
	v_mfma_f32_32x32x16_bf16 v[104:119], v[92:95], v[188:191], v[104:119]
	v_mfma_f32_32x32x16_bf16 v[128:143], v[92:95], v[192:195], v[128:143]
	v_mfma_f32_32x32x16_bf16 v[196:211], v[96:99], v[188:191], v[196:211]
	v_mfma_f32_32x32x16_bf16 v[236:251], v[96:99], v[192:195], v[236:251]
	s_waitcnt lgkmcnt(0)
	s_barrier
	v_mfma_f32_32x32x16_bf16 v[104:119], v[100:103], v[212:215], v[104:119]
	v_mfma_f32_32x32x16_bf16 v[128:143], v[100:103], v[216:219], v[128:143]
	v_mfma_f32_32x32x16_bf16 v[196:211], v[144:147], v[212:215], v[196:211]
	v_mfma_f32_32x32x16_bf16 v[236:251], v[144:147], v[216:219], v[236:251]
	v_mfma_f32_32x32x16_bf16 v[104:119], v[148:151], v[220:223], v[104:119]
	v_mfma_f32_32x32x16_bf16 v[128:143], v[148:151], v[224:227], v[128:143]
	v_mfma_f32_32x32x16_bf16 v[196:211], v[152:155], v[220:223], v[196:211]
	v_mfma_f32_32x32x16_bf16 v[236:251], v[152:155], v[224:227], v[236:251]
	v_mfma_f32_32x32x16_bf16 v[104:119], v[180:183], v[228:231], v[104:119]
	v_mfma_f32_32x32x16_bf16 v[128:143], v[180:183], v[252:255], v[128:143]
	v_mfma_f32_32x32x16_bf16 v[196:211], v[184:187], v[228:231], v[196:211]
	v_mfma_f32_32x32x16_bf16 v[236:251], v[184:187], v[252:255], v[236:251]
	s_waitcnt vmcnt(0) lgkmcnt(0)
	s_barrier
	s_branch .LBB0_187
.Lg1_loop_w3:
	ds_read_b128 v[92:95], v84 offset:0
	ds_read_b128 v[96:99], v84 offset:4096
	ds_read_b128 v[188:191], v85 offset:0
	ds_read_b128 v[192:195], v85 offset:4096
	ds_read_b128 v[100:103], v86 offset:0
	ds_read_b128 v[144:147], v86 offset:4096
	ds_read_b128 v[212:215], v87 offset:0
	ds_read_b128 v[216:219], v87 offset:4096
	ds_read_b128 v[148:151], v88 offset:0
	ds_read_b128 v[152:155], v88 offset:4096
	ds_read_b128 v[220:223], v89 offset:0
	ds_read_b128 v[224:227], v89 offset:4096
	ds_read_b128 v[180:183], v90 offset:0
	ds_read_b128 v[184:187], v90 offset:4096
	ds_read_b128 v[228:231], v91 offset:0
	ds_read_b128 v[252:255], v91 offset:4096
	s_waitcnt lgkmcnt(12)
	v_mfma_f32_32x32x16_bf16 v[18:33], v[92:95], v[188:191], v[18:33]
	v_mfma_f32_32x32x16_bf16 v[50:65], v[92:95], v[192:195], v[50:65]
	v_mfma_f32_32x32x16_bf16 v[2:17], v[96:99], v[188:191], v[2:17]
	v_mfma_f32_32x32x16_bf16 v[34:49], v[96:99], v[192:195], v[34:49]
	s_waitcnt lgkmcnt(0)
	s_barrier
	v_mfma_f32_32x32x16_bf16 v[18:33], v[100:103], v[212:215], v[18:33]
	s_mov_b32 m0, s1
	v_mfma_f32_32x32x16_bf16 v[50:65], v[100:103], v[216:219], v[50:65]
	global_load_lds_dwordx4 v[66:67], off
	v_mfma_f32_32x32x16_bf16 v[2:17], v[144:147], v[212:215], v[2:17]
	s_add_i32 m0, s1, 0x400
	v_mfma_f32_32x32x16_bf16 v[34:49], v[144:147], v[216:219], v[34:49]
	global_load_lds_dwordx4 v[70:71], off
	v_mfma_f32_32x32x16_bf16 v[18:33], v[148:151], v[220:223], v[18:33]
	s_add_i32 m0, s1, 0x800
	v_mfma_f32_32x32x16_bf16 v[50:65], v[148:151], v[224:227], v[50:65]
	global_load_lds_dwordx4 v[74:75], off
	v_mfma_f32_32x32x16_bf16 v[2:17], v[152:155], v[220:223], v[2:17]
	s_add_i32 m0, s1, 0xc00
	v_mfma_f32_32x32x16_bf16 v[34:49], v[152:155], v[224:227], v[34:49]
	global_load_lds_dwordx4 v[78:79], off
	v_mfma_f32_32x32x16_bf16 v[18:33], v[180:183], v[228:231], v[18:33]
	s_mov_b32 m0, s8
	v_mfma_f32_32x32x16_bf16 v[50:65], v[180:183], v[252:255], v[50:65]
	global_load_lds_dwordx4 v[68:69], off
	v_lshl_add_u64 v[68:69], v[68:69], 0, s[34:35]
	v_mfma_f32_32x32x16_bf16 v[2:17], v[184:187], v[228:231], v[2:17]
	s_mov_b32 m0, s9
	v_mfma_f32_32x32x16_bf16 v[34:49], v[184:187], v[252:255], v[34:49]
	global_load_lds_dwordx4 v[72:73], off
	v_lshl_add_u64 v[72:73], v[72:73], 0, s[34:35]
	s_waitcnt vmcnt(8)
	s_barrier
	ds_read_b128 v[92:95], v84 offset:32768
	ds_read_b128 v[96:99], v84 offset:36864
	ds_read_b128 v[100:103], v86 offset:32768
	ds_read_b128 v[144:147], v86 offset:36864
	ds_read_b128 v[148:151], v88 offset:32768
	ds_read_b128 v[152:155], v88 offset:36864
	ds_read_b128 v[180:183], v90 offset:32768
	ds_read_b128 v[184:187], v90 offset:36864
	s_waitcnt lgkmcnt(6)
	v_mfma_f32_32x32x16_bf16 v[104:119], v[92:95], v[188:191], v[104:119]
	v_mfma_f32_32x32x16_bf16 v[128:143], v[92:95], v[192:195], v[128:143]
	v_mfma_f32_32x32x16_bf16 v[196:211], v[96:99], v[188:191], v[196:211]
	v_mfma_f32_32x32x16_bf16 v[236:251], v[96:99], v[192:195], v[236:251]
	s_waitcnt lgkmcnt(0)
	s_barrier
	v_mfma_f32_32x32x16_bf16 v[104:119], v[100:103], v[212:215], v[104:119]
	s_mov_b32 m0, s6
	v_lshl_add_u64 v[82:83], v[66:67], 0, s[26:27]
	v_mfma_f32_32x32x16_bf16 v[128:143], v[100:103], v[216:219], v[128:143]
	global_load_lds_dwordx4 v[82:83], off
	v_lshl_add_u64 v[66:67], v[66:67], 0, s[34:35]
	v_mfma_f32_32x32x16_bf16 v[196:211], v[144:147], v[212:215], v[196:211]
	s_mov_b32 m0, s13
	v_lshl_add_u64 v[82:83], v[70:71], 0, s[26:27]
	v_mfma_f32_32x32x16_bf16 v[236:251], v[144:147], v[216:219], v[236:251]
	global_load_lds_dwordx4 v[82:83], off
	v_lshl_add_u64 v[70:71], v[70:71], 0, s[34:35]
	v_mfma_f32_32x32x16_bf16 v[104:119], v[148:151], v[220:223], v[104:119]
	s_mov_b32 m0, s15
	v_lshl_add_u64 v[82:83], v[74:75], 0, s[26:27]
	v_mfma_f32_32x32x16_bf16 v[128:143], v[148:151], v[224:227], v[128:143]
	global_load_lds_dwordx4 v[82:83], off
	v_lshl_add_u64 v[74:75], v[74:75], 0, s[34:35]
	v_mfma_f32_32x32x16_bf16 v[196:211], v[152:155], v[220:223], v[196:211]
	s_mov_b32 m0, s17
	v_lshl_add_u64 v[82:83], v[78:79], 0, s[26:27]
	v_mfma_f32_32x32x16_bf16 v[236:251], v[152:155], v[224:227], v[236:251]
	global_load_lds_dwordx4 v[82:83], off
	v_lshl_add_u64 v[78:79], v[78:79], 0, s[34:35]
	v_mfma_f32_32x32x16_bf16 v[104:119], v[180:183], v[228:231], v[104:119]
	s_mov_b32 m0, s10
	v_mfma_f32_32x32x16_bf16 v[128:143], v[180:183], v[252:255], v[128:143]
	global_load_lds_dwordx4 v[76:77], off
	v_lshl_add_u64 v[76:77], v[76:77], 0, s[34:35]
	v_mfma_f32_32x32x16_bf16 v[196:211], v[184:187], v[228:231], v[196:211]
	s_mov_b32 m0, s11
	v_mfma_f32_32x32x16_bf16 v[236:251], v[184:187], v[252:255], v[236:251]
	global_load_lds_dwordx4 v[80:81], off
	v_lshl_add_u64 v[80:81], v[80:81], 0, s[34:35]
	s_waitcnt vmcnt(8)
	s_barrier
	ds_read_b128 v[92:95], v84 offset:0
	ds_read_b128 v[96:99], v84 offset:4096
	ds_read_b128 v[188:191], v85 offset:32768
	ds_read_b128 v[192:195], v85 offset:36864
	ds_read_b128 v[100:103], v86 offset:0
	ds_read_b128 v[144:147], v86 offset:4096
	ds_read_b128 v[212:215], v87 offset:32768
	ds_read_b128 v[216:219], v87 offset:36864
	ds_read_b128 v[148:151], v88 offset:0
	ds_read_b128 v[152:155], v88 offset:4096
	ds_read_b128 v[220:223], v89 offset:32768
	ds_read_b128 v[224:227], v89 offset:36864
	ds_read_b128 v[180:183], v90 offset:0
	ds_read_b128 v[184:187], v90 offset:4096
	ds_read_b128 v[228:231], v91 offset:32768
	ds_read_b128 v[252:255], v91 offset:36864
	s_waitcnt lgkmcnt(12)
	v_mfma_f32_32x32x16_bf16 v[18:33], v[92:95], v[188:191], v[18:33]
	v_mfma_f32_32x32x16_bf16 v[50:65], v[92:95], v[192:195], v[50:65]
	v_mfma_f32_32x32x16_bf16 v[2:17], v[96:99], v[188:191], v[2:17]
	v_mfma_f32_32x32x16_bf16 v[34:49], v[96:99], v[192:195], v[34:49]
	s_waitcnt lgkmcnt(0)
	s_barrier
	v_mfma_f32_32x32x16_bf16 v[18:33], v[100:103], v[212:215], v[18:33]
	s_mov_b32 m0, s1
	v_mfma_f32_32x32x16_bf16 v[50:65], v[100:103], v[216:219], v[50:65]
	global_load_lds_dwordx4 v[66:67], off
	v_mfma_f32_32x32x16_bf16 v[2:17], v[144:147], v[212:215], v[2:17]
	s_add_i32 m0, s1, 0x400
	v_mfma_f32_32x32x16_bf16 v[34:49], v[144:147], v[216:219], v[34:49]
	global_load_lds_dwordx4 v[70:71], off
	v_mfma_f32_32x32x16_bf16 v[18:33], v[148:151], v[220:223], v[18:33]
	s_add_i32 m0, s1, 0x800
	v_mfma_f32_32x32x16_bf16 v[50:65], v[148:151], v[224:227], v[50:65]
	global_load_lds_dwordx4 v[74:75], off
	v_mfma_f32_32x32x16_bf16 v[2:17], v[152:155], v[220:223], v[2:17]
	s_add_i32 m0, s1, 0xc00
	v_mfma_f32_32x32x16_bf16 v[34:49], v[152:155], v[224:227], v[34:49]
	global_load_lds_dwordx4 v[78:79], off
	v_mfma_f32_32x32x16_bf16 v[18:33], v[180:183], v[228:231], v[18:33]
	s_mov_b32 m0, s7
	v_mfma_f32_32x32x16_bf16 v[50:65], v[180:183], v[252:255], v[50:65]
	global_load_lds_dwordx4 v[68:69], off
	v_lshl_add_u64 v[68:69], v[68:69], 0, s[34:35]
	v_mfma_f32_32x32x16_bf16 v[2:17], v[184:187], v[228:231], v[2:17]
	s_mov_b32 m0, s14
	v_mfma_f32_32x32x16_bf16 v[34:49], v[184:187], v[252:255], v[34:49]
	global_load_lds_dwordx4 v[72:73], off
	v_lshl_add_u64 v[72:73], v[72:73], 0, s[34:35]
	s_waitcnt vmcnt(8)
	s_barrier
	ds_read_b128 v[92:95], v84 offset:32768
	ds_read_b128 v[96:99], v84 offset:36864
	ds_read_b128 v[100:103], v86 offset:32768
	ds_read_b128 v[144:147], v86 offset:36864
	ds_read_b128 v[148:151], v88 offset:32768
	ds_read_b128 v[152:155], v88 offset:36864
	ds_read_b128 v[180:183], v90 offset:32768
	ds_read_b128 v[184:187], v90 offset:36864
	s_waitcnt lgkmcnt(6)
	v_mfma_f32_32x32x16_bf16 v[104:119], v[92:95], v[188:191], v[104:119]
	v_mfma_f32_32x32x16_bf16 v[128:143], v[92:95], v[192:195], v[128:143]
	v_mfma_f32_32x32x16_bf16 v[196:211], v[96:99], v[188:191], v[196:211]
	v_mfma_f32_32x32x16_bf16 v[236:251], v[96:99], v[192:195], v[236:251]
	s_waitcnt lgkmcnt(0)
	s_barrier
	v_mfma_f32_32x32x16_bf16 v[104:119], v[100:103], v[212:215], v[104:119]
	s_mov_b32 m0, s6
	v_lshl_add_u64 v[82:83], v[66:67], 0, s[26:27]
	v_mfma_f32_32x32x16_bf16 v[128:143], v[100:103], v[216:219], v[128:143]
	global_load_lds_dwordx4 v[82:83], off
	v_lshl_add_u64 v[66:67], v[66:67], 0, s[34:35]
	v_mfma_f32_32x32x16_bf16 v[196:211], v[144:147], v[212:215], v[196:211]
	s_mov_b32 m0, s13
	v_lshl_add_u64 v[82:83], v[70:71], 0, s[26:27]
	v_mfma_f32_32x32x16_bf16 v[236:251], v[144:147], v[216:219], v[236:251]
	global_load_lds_dwordx4 v[82:83], off
	v_lshl_add_u64 v[70:71], v[70:71], 0, s[34:35]
	v_mfma_f32_32x32x16_bf16 v[104:119], v[148:151], v[220:223], v[104:119]
	s_mov_b32 m0, s15
	v_lshl_add_u64 v[82:83], v[74:75], 0, s[26:27]
	v_mfma_f32_32x32x16_bf16 v[128:143], v[148:151], v[224:227], v[128:143]
	global_load_lds_dwordx4 v[82:83], off
	v_lshl_add_u64 v[74:75], v[74:75], 0, s[34:35]
	v_mfma_f32_32x32x16_bf16 v[196:211], v[152:155], v[220:223], v[196:211]
	s_mov_b32 m0, s17
	v_lshl_add_u64 v[82:83], v[78:79], 0, s[26:27]
	v_mfma_f32_32x32x16_bf16 v[236:251], v[152:155], v[224:227], v[236:251]
	global_load_lds_dwordx4 v[82:83], off
	v_lshl_add_u64 v[78:79], v[78:79], 0, s[34:35]
	v_mfma_f32_32x32x16_bf16 v[104:119], v[180:183], v[228:231], v[104:119]
	s_mov_b32 m0, s16
	v_mfma_f32_32x32x16_bf16 v[128:143], v[180:183], v[252:255], v[128:143]
	global_load_lds_dwordx4 v[76:77], off
	v_lshl_add_u64 v[76:77], v[76:77], 0, s[34:35]
	v_mfma_f32_32x32x16_bf16 v[196:211], v[184:187], v[228:231], v[196:211]
	s_mov_b32 m0, s25
	v_mfma_f32_32x32x16_bf16 v[236:251], v[184:187], v[252:255], v[236:251]
	global_load_lds_dwordx4 v[80:81], off
	v_lshl_add_u64 v[80:81], v[80:81], 0, s[34:35]
	s_waitcnt vmcnt(8)
	s_barrier
	s_add_i32 s12, s12, 2
	s_cmp_lt_u32 s12, 14
	s_cbranch_scc1 .Lg1_loop_w3
	ds_read_b128 v[92:95], v84 offset:0
	ds_read_b128 v[96:99], v84 offset:4096
	ds_read_b128 v[188:191], v85 offset:0
	ds_read_b128 v[192:195], v85 offset:4096
	ds_read_b128 v[100:103], v86 offset:0
	ds_read_b128 v[144:147], v86 offset:4096
	ds_read_b128 v[212:215], v87 offset:0
	ds_read_b128 v[216:219], v87 offset:4096
	ds_read_b128 v[148:151], v88 offset:0
	ds_read_b128 v[152:155], v88 offset:4096
	ds_read_b128 v[220:223], v89 offset:0
	ds_read_b128 v[224:227], v89 offset:4096
	ds_read_b128 v[180:183], v90 offset:0
	ds_read_b128 v[184:187], v90 offset:4096
	ds_read_b128 v[228:231], v91 offset:0
	ds_read_b128 v[252:255], v91 offset:4096
	s_waitcnt lgkmcnt(12)
	v_mfma_f32_32x32x16_bf16 v[18:33], v[92:95], v[188:191], v[18:33]
	v_mfma_f32_32x32x16_bf16 v[50:65], v[92:95], v[192:195], v[50:65]
	v_mfma_f32_32x32x16_bf16 v[2:17], v[96:99], v[188:191], v[2:17]
	v_mfma_f32_32x32x16_bf16 v[34:49], v[96:99], v[192:195], v[34:49]
	s_waitcnt lgkmcnt(0)
	s_barrier
	v_mfma_f32_32x32x16_bf16 v[18:33], v[100:103], v[212:215], v[18:33]
	s_mov_b32 m0, s1
	v_mfma_f32_32x32x16_bf16 v[50:65], v[100:103], v[216:219], v[50:65]
	global_load_lds_dwordx4 v[66:67], off
	v_mfma_f32_32x32x16_bf16 v[2:17], v[144:147], v[212:215], v[2:17]
	s_add_i32 m0, s1, 0x400
	v_mfma_f32_32x32x16_bf16 v[34:49], v[144:147], v[216:219], v[34:49]
	global_load_lds_dwordx4 v[70:71], off
	v_mfma_f32_32x32x16_bf16 v[18:33], v[148:151], v[220:223], v[18:33]
	v_mfma_f32_32x32x16_bf16 v[50:65], v[148:151], v[224:227], v[50:65]
	v_mfma_f32_32x32x16_bf16 v[2:17], v[152:155], v[220:223], v[2:17]
	s_add_i32 m0, s1, 0x800
	v_mfma_f32_32x32x16_bf16 v[34:49], v[152:155], v[224:227], v[34:49]
	global_load_lds_dwordx4 v[74:75], off
	v_mfma_f32_32x32x16_bf16 v[18:33], v[180:183], v[228:231], v[18:33]
	s_add_i32 m0, s1, 0xc00
	v_mfma_f32_32x32x16_bf16 v[50:65], v[180:183], v[252:255], v[50:65]
	global_load_lds_dwordx4 v[78:79], off
	v_mfma_f32_32x32x16_bf16 v[2:17], v[184:187], v[228:231], v[2:17]
	v_mfma_f32_32x32x16_bf16 v[34:49], v[184:187], v[252:255], v[34:49]
	s_waitcnt vmcnt(4)
	s_barrier
	ds_read_b128 v[92:95], v84 offset:32768
	ds_read_b128 v[96:99], v84 offset:36864
	ds_read_b128 v[100:103], v86 offset:32768
	ds_read_b128 v[144:147], v86 offset:36864
	ds_read_b128 v[148:151], v88 offset:32768
	ds_read_b128 v[152:155], v88 offset:36864
	ds_read_b128 v[180:183], v90 offset:32768
	ds_read_b128 v[184:187], v90 offset:36864
	s_waitcnt lgkmcnt(6)
	v_mfma_f32_32x32x16_bf16 v[104:119], v[92:95], v[188:191], v[104:119]
	v_mfma_f32_32x32x16_bf16 v[128:143], v[92:95], v[192:195], v[128:143]
	v_mfma_f32_32x32x16_bf16 v[196:211], v[96:99], v[188:191], v[196:211]
	v_mfma_f32_32x32x16_bf16 v[236:251], v[96:99], v[192:195], v[236:251]
	s_waitcnt lgkmcnt(0)
	s_barrier
	v_mfma_f32_32x32x16_bf16 v[104:119], v[100:103], v[212:215], v[104:119]
	s_mov_b32 m0, s6
	v_lshl_add_u64 v[82:83], v[66:67], 0, s[26:27]
	v_mfma_f32_32x32x16_bf16 v[128:143], v[100:103], v[216:219], v[128:143]
	global_load_lds_dwordx4 v[82:83], off
	v_lshl_add_u64 v[66:67], v[66:67], 0, s[34:35]
	v_mfma_f32_32x32x16_bf16 v[196:211], v[144:147], v[212:215], v[196:211]
	s_mov_b32 m0, s13
	v_lshl_add_u64 v[82:83], v[70:71], 0, s[26:27]
	v_mfma_f32_32x32x16_bf16 v[236:251], v[144:147], v[216:219], v[236:251]
	global_load_lds_dwordx4 v[82:83], off
	v_lshl_add_u64 v[70:71], v[70:71], 0, s[34:35]
	v_mfma_f32_32x32x16_bf16 v[104:119], v[148:151], v[220:223], v[104:119]
	v_mfma_f32_32x32x16_bf16 v[128:143], v[148:151], v[224:227], v[128:143]
	v_mfma_f32_32x32x16_bf16 v[196:211], v[152:155], v[220:223], v[196:211]
	s_mov_b32 m0, s15
	v_lshl_add_u64 v[82:83], v[74:75], 0, s[26:27]
	v_mfma_f32_32x32x16_bf16 v[236:251], v[152:155], v[224:227], v[236:251]
	global_load_lds_dwordx4 v[82:83], off
	v_lshl_add_u64 v[74:75], v[74:75], 0, s[34:35]
	v_mfma_f32_32x32x16_bf16 v[104:119], v[180:183], v[228:231], v[104:119]
	s_mov_b32 m0, s17
	v_lshl_add_u64 v[82:83], v[78:79], 0, s[26:27]
	v_mfma_f32_32x32x16_bf16 v[128:143], v[180:183], v[252:255], v[128:143]
	global_load_lds_dwordx4 v[82:83], off
	v_lshl_add_u64 v[78:79], v[78:79], 0, s[34:35]
	v_mfma_f32_32x32x16_bf16 v[196:211], v[184:187], v[228:231], v[196:211]
	v_mfma_f32_32x32x16_bf16 v[236:251], v[184:187], v[252:255], v[236:251]
	s_waitcnt vmcnt(4)
	s_barrier
	ds_read_b128 v[92:95], v84 offset:0
	ds_read_b128 v[96:99], v84 offset:4096
	ds_read_b128 v[188:191], v85 offset:32768
	ds_read_b128 v[192:195], v85 offset:36864
	ds_read_b128 v[100:103], v86 offset:0
	ds_read_b128 v[144:147], v86 offset:4096
	ds_read_b128 v[212:215], v87 offset:32768
	ds_read_b128 v[216:219], v87 offset:36864
	ds_read_b128 v[148:151], v88 offset:0
	ds_read_b128 v[152:155], v88 offset:4096
	ds_read_b128 v[220:223], v89 offset:32768
	ds_read_b128 v[224:227], v89 offset:36864
	ds_read_b128 v[180:183], v90 offset:0
	ds_read_b128 v[184:187], v90 offset:4096
	ds_read_b128 v[228:231], v91 offset:32768
	ds_read_b128 v[252:255], v91 offset:36864
	s_waitcnt lgkmcnt(12)
	v_mfma_f32_32x32x16_bf16 v[18:33], v[92:95], v[188:191], v[18:33]
	v_mfma_f32_32x32x16_bf16 v[50:65], v[92:95], v[192:195], v[50:65]
	v_mfma_f32_32x32x16_bf16 v[2:17], v[96:99], v[188:191], v[2:17]
	v_mfma_f32_32x32x16_bf16 v[34:49], v[96:99], v[192:195], v[34:49]
	s_waitcnt lgkmcnt(0)
	s_barrier
	v_mfma_f32_32x32x16_bf16 v[18:33], v[100:103], v[212:215], v[18:33]
	v_mfma_f32_32x32x16_bf16 v[50:65], v[100:103], v[216:219], v[50:65]
	v_mfma_f32_32x32x16_bf16 v[2:17], v[144:147], v[212:215], v[2:17]
	v_mfma_f32_32x32x16_bf16 v[34:49], v[144:147], v[216:219], v[34:49]
	v_mfma_f32_32x32x16_bf16 v[18:33], v[148:151], v[220:223], v[18:33]
	v_mfma_f32_32x32x16_bf16 v[50:65], v[148:151], v[224:227], v[50:65]
	v_mfma_f32_32x32x16_bf16 v[2:17], v[152:155], v[220:223], v[2:17]
	v_mfma_f32_32x32x16_bf16 v[34:49], v[152:155], v[224:227], v[34:49]
	v_mfma_f32_32x32x16_bf16 v[18:33], v[180:183], v[228:231], v[18:33]
	v_mfma_f32_32x32x16_bf16 v[50:65], v[180:183], v[252:255], v[50:65]
	v_mfma_f32_32x32x16_bf16 v[2:17], v[184:187], v[228:231], v[2:17]
	v_mfma_f32_32x32x16_bf16 v[34:49], v[184:187], v[252:255], v[34:49]
	s_waitcnt vmcnt(0)
	s_barrier
	ds_read_b128 v[92:95], v84 offset:32768
	ds_read_b128 v[96:99], v84 offset:36864
	ds_read_b128 v[100:103], v86 offset:32768
	ds_read_b128 v[144:147], v86 offset:36864
	ds_read_b128 v[148:151], v88 offset:32768
	ds_read_b128 v[152:155], v88 offset:36864
	ds_read_b128 v[180:183], v90 offset:32768
	ds_read_b128 v[184:187], v90 offset:36864
	s_waitcnt lgkmcnt(6)
	v_mfma_f32_32x32x16_bf16 v[104:119], v[92:95], v[188:191], v[104:119]
	v_mfma_f32_32x32x16_bf16 v[128:143], v[92:95], v[192:195], v[128:143]
	v_mfma_f32_32x32x16_bf16 v[196:211], v[96:99], v[188:191], v[196:211]
	v_mfma_f32_32x32x16_bf16 v[236:251], v[96:99], v[192:195], v[236:251]
	s_waitcnt lgkmcnt(0)
	s_barrier
	v_mfma_f32_32x32x16_bf16 v[104:119], v[100:103], v[212:215], v[104:119]
	v_mfma_f32_32x32x16_bf16 v[128:143], v[100:103], v[216:219], v[128:143]
	v_mfma_f32_32x32x16_bf16 v[196:211], v[144:147], v[212:215], v[196:211]
	v_mfma_f32_32x32x16_bf16 v[236:251], v[144:147], v[216:219], v[236:251]
	v_mfma_f32_32x32x16_bf16 v[104:119], v[148:151], v[220:223], v[104:119]
	v_mfma_f32_32x32x16_bf16 v[128:143], v[148:151], v[224:227], v[128:143]
	v_mfma_f32_32x32x16_bf16 v[196:211], v[152:155], v[220:223], v[196:211]
	v_mfma_f32_32x32x16_bf16 v[236:251], v[152:155], v[224:227], v[236:251]
	v_mfma_f32_32x32x16_bf16 v[104:119], v[180:183], v[228:231], v[104:119]
	v_mfma_f32_32x32x16_bf16 v[128:143], v[180:183], v[252:255], v[128:143]
	v_mfma_f32_32x32x16_bf16 v[196:211], v[184:187], v[228:231], v[196:211]
	v_mfma_f32_32x32x16_bf16 v[236:251], v[184:187], v[252:255], v[236:251]
	s_waitcnt vmcnt(0) lgkmcnt(0)
	s_barrier
